# v045_rotate
# baseline (speedup 1.0000x reference)
; #define WAIT_V(n) asm volatile("s_waitcnt vmcnt(" #n ")" ::: "memory")
; #define WAIT_L(n) asm volatile("s_waitcnt lgkmcnt(" #n ")" ::: "memory")
; #define BAR __builtin_amdgcn_s_barrier()
; #define SCHED __builtin_amdgcn_sched_barrier(0)
; template <int K>
; __device__ __forceinline__ void gemm_mainloop(const bf16* __restrict__ A, const bf16* __restrict__ Bt, int brow, int bcol,
;                                               f32x4 (&acc)[2][2][4][2], const int tidx) {
;     ...
;   for (int t = 0; t < nt - 2; t += 2) {
;     LDB(B0, 0, 0); SCHED; LDA(At, 0, 0); STAGE(SA(1, 1), A, brow + HALF, t + 1);
;     WAIT_L(8); BAR; WAIT_L(0); MMA(0, 0, At, B0); BAR; SCHED;
;     LDB(B1, 0, 1); STAGE(SB(0, 0), Bt, bcol, t + 2);
;     BAR; WAIT_L(0); MMA(0, 1, At, B1); BAR;
;     LDA(At, 0, 1); STAGE(SA(0, 0), A, brow, t + 2);
;     BAR; WAIT_L(0); MMA(1, 0, At, B0); BAR; SCHED;
;     STAGE(SB(0, 1), Bt, bcol + HALF, t + 2);
;     WAIT_V(6); BAR; MMA(1, 1, At, B1); BAR;
.LBB0_42:
	s_barrier
	ds_read_b128 v[172:175], v168
	ds_read_b128 v[176:179], v168 offset:1024
	ds_read_b128 v[180:183], v168 offset:2048
	ds_read_b128 v[184:187], v168 offset:3072
	v_add_u32_e32 v169, 0xc000, v154
	v_lshl_add_u64 v[208:209], s[86:87], 0, v[142:143]
	v_readfirstlane_b32 s17, v169
	v_lshl_add_u64 v[170:171], v[208:209], 0, vcc
	s_mov_b32 m0, s17
	ds_read_b128 v[188:191], v152
	ds_read_b128 v[192:195], v152 offset:1024
	ds_read_b128 v[196:199], v151
	ds_read_b128 v[200:203], v151 offset:1024
	ds_read_b128 v[204:207], v150
	ds_read_b128 v[222:225], v150 offset:1024
	ds_read_b128 v[226:229], v149
	ds_read_b128 v[230:233], v149 offset:1024
	global_load_lds_dwordx4 v[170:171], off
	v_add_u32_e32 v170, 0xe000, v154
	v_lshl_add_u64 v[212:213], s[86:87], 0, v[144:145]
	v_readfirstlane_b32 s17, v170
	v_lshl_add_u64 v[216:217], v[212:213], 0, vcc
	s_mov_b32 m0, s17
	s_nop 0
	global_load_lds_dwordx4 v[216:217], off
	s_waitcnt lgkmcnt(8)
	s_barrier
	s_waitcnt lgkmcnt(0)
	s_setprio 1
	s_waitcnt lgkmcnt(0)
	v_mfma_f32_16x16x32_bf16 v[126:129], v[188:191], v[172:175], v[126:129]
	v_mfma_f32_16x16x32_bf16 v[122:125], v[188:191], v[180:183], v[122:125]
	v_mfma_f32_16x16x32_bf16 v[118:121], v[196:199], v[172:175], v[118:121]
	v_mfma_f32_16x16x32_bf16 v[114:117], v[196:199], v[180:183], v[114:117]
	v_mfma_f32_16x16x32_bf16 v[110:113], v[204:207], v[172:175], v[110:113]
	v_mfma_f32_16x16x32_bf16 v[106:109], v[204:207], v[180:183], v[106:109]
	v_mfma_f32_16x16x32_bf16 v[102:105], v[226:229], v[172:175], v[102:105]
	v_mfma_f32_16x16x32_bf16 v[98:101], v[226:229], v[180:183], v[98:101]
	v_mfma_f32_16x16x32_bf16 v[126:129], v[192:195], v[176:179], v[126:129]
	v_mfma_f32_16x16x32_bf16 v[122:125], v[192:195], v[184:187], v[122:125]
	v_mfma_f32_16x16x32_bf16 v[118:121], v[200:203], v[176:179], v[118:121]
	v_mfma_f32_16x16x32_bf16 v[114:117], v[200:203], v[184:187], v[114:117]
	v_mfma_f32_16x16x32_bf16 v[110:113], v[222:225], v[176:179], v[110:113]
	v_mfma_f32_16x16x32_bf16 v[106:109], v[222:225], v[184:187], v[106:109]
	v_mfma_f32_16x16x32_bf16 v[102:105], v[230:233], v[176:179], v[102:105]
	v_mfma_f32_16x16x32_bf16 v[98:101], v[230:233], v[184:187], v[98:101]
	s_setprio 0
	s_barrier
	v_lshl_add_u64 v[216:217], s[86:87], 0, v[138:139]
	v_readfirstlane_b32 s17, v148
	v_lshl_add_u64 v[218:219], v[216:217], 0, s[92:93]
	s_mov_b32 m0, s17
	v_add_u32_e32 v171, 0x2000, v148
	ds_read_b128 v[234:237], v164
	ds_read_b128 v[238:241], v164 offset:1024
	ds_read_b128 v[242:245], v164 offset:2048
	ds_read_b128 v[246:249], v164 offset:3072
	global_load_lds_dwordx4 v[218:219], off
	v_lshl_add_u64 v[218:219], s[86:87], 0, v[140:141]
	v_readfirstlane_b32 s17, v171
	v_lshl_add_u64 v[250:251], v[218:219], 0, s[92:93]
	s_mov_b32 m0, s17
	s_nop 0
	global_load_lds_dwordx4 v[250:251], off
	s_barrier
	s_waitcnt lgkmcnt(0)
	s_setprio 1
	s_waitcnt lgkmcnt(0)
	v_mfma_f32_16x16x32_bf16 v[92:95], v[188:191], v[234:237], v[92:95]
	v_mfma_f32_16x16x32_bf16 v[88:91], v[188:191], v[242:245], v[88:91]
	v_mfma_f32_16x16x32_bf16 v[84:87], v[196:199], v[234:237], v[84:87]
	v_mfma_f32_16x16x32_bf16 v[80:83], v[196:199], v[242:245], v[80:83]
	v_mfma_f32_16x16x32_bf16 v[76:79], v[204:207], v[234:237], v[76:79]
	v_mfma_f32_16x16x32_bf16 v[72:75], v[204:207], v[242:245], v[72:75]
	v_mfma_f32_16x16x32_bf16 v[68:71], v[226:229], v[234:237], v[68:71]
	v_mfma_f32_16x16x32_bf16 v[64:67], v[226:229], v[242:245], v[64:67]
	v_mfma_f32_16x16x32_bf16 v[92:95], v[192:195], v[238:241], v[92:95]
	v_mfma_f32_16x16x32_bf16 v[88:91], v[192:195], v[246:249], v[88:91]
	v_mfma_f32_16x16x32_bf16 v[84:87], v[200:203], v[238:241], v[84:87]
	v_mfma_f32_16x16x32_bf16 v[80:83], v[200:203], v[246:249], v[80:83]
	v_mfma_f32_16x16x32_bf16 v[76:79], v[222:225], v[238:241], v[76:79]
	v_mfma_f32_16x16x32_bf16 v[72:75], v[222:225], v[246:249], v[72:75]
	v_mfma_f32_16x16x32_bf16 v[68:71], v[230:233], v[238:241], v[68:71]
	v_mfma_f32_16x16x32_bf16 v[64:67], v[230:233], v[246:249], v[64:67]
	s_setprio 0
	v_readfirstlane_b32 s17, v154
	v_lshl_add_u64 v[250:251], v[208:209], 0, s[38:39]
	s_mov_b32 m0, s17
	v_readfirstlane_b32 s17, v155
	s_barrier
	ds_read_b128 v[188:191], v152 offset:16384
	ds_read_b128 v[192:195], v152 offset:17408
	ds_read_b128 v[196:199], v151 offset:16384
	ds_read_b128 v[200:203], v151 offset:17408
	ds_read_b128 v[204:207], v150 offset:16384
	ds_read_b128 v[222:225], v150 offset:17408
	ds_read_b128 v[226:229], v149 offset:16384
	ds_read_b128 v[230:233], v149 offset:17408
	global_load_lds_dwordx4 v[250:251], off
	v_lshl_add_u64 v[250:251], v[212:213], 0, s[38:39]
	s_mov_b32 m0, s17
	s_nop 0
	global_load_lds_dwordx4 v[250:251], off
	s_barrier
	s_waitcnt lgkmcnt(0)
	s_setprio 1
	s_waitcnt lgkmcnt(0)
	v_mfma_f32_16x16x32_bf16 v[60:63], v[188:191], v[172:175], v[60:63]
	v_mfma_f32_16x16x32_bf16 v[56:59], v[188:191], v[180:183], v[56:59]
	v_mfma_f32_16x16x32_bf16 v[52:55], v[196:199], v[172:175], v[52:55]
	v_mfma_f32_16x16x32_bf16 v[48:51], v[196:199], v[180:183], v[48:51]
	v_mfma_f32_16x16x32_bf16 v[44:47], v[204:207], v[172:175], v[44:47]
	v_mfma_f32_16x16x32_bf16 v[40:43], v[204:207], v[180:183], v[40:43]
	v_mfma_f32_16x16x32_bf16 v[36:39], v[226:229], v[172:175], v[36:39]
	v_mfma_f32_16x16x32_bf16 v[32:35], v[226:229], v[180:183], v[32:35]
	v_mfma_f32_16x16x32_bf16 v[60:63], v[192:195], v[176:179], v[60:63]
	v_mfma_f32_16x16x32_bf16 v[56:59], v[192:195], v[184:187], v[56:59]
	v_mfma_f32_16x16x32_bf16 v[52:55], v[200:203], v[176:179], v[52:55]
	v_mfma_f32_16x16x32_bf16 v[48:51], v[200:203], v[184:187], v[48:51]
	v_mfma_f32_16x16x32_bf16 v[44:47], v[222:225], v[176:179], v[44:47]
	v_mfma_f32_16x16x32_bf16 v[40:43], v[222:225], v[184:187], v[40:43]
	v_mfma_f32_16x16x32_bf16 v[36:39], v[230:233], v[176:179], v[36:39]
	v_mfma_f32_16x16x32_bf16 v[32:35], v[230:233], v[184:187], v[32:35]
	s_setprio 0
	s_barrier
; #define WAIT_V(n) asm volatile("s_waitcnt vmcnt(" #n ")" ::: "memory")
; #define WAIT_L(n) asm volatile("s_waitcnt lgkmcnt(" #n ")" ::: "memory")
; #define BAR __builtin_amdgcn_s_barrier()
; #define SCHED __builtin_amdgcn_sched_barrier(0)
; template <int K>
; __device__ __forceinline__ void gemm_mainloop(const bf16* __restrict__ A, const bf16* __restrict__ Bt, int brow, int bcol,
;                                               f32x4 (&acc)[2][2][4][2], const int tidx) {
;     ...
;     STAGE(SB(0, 1), Bt, bcol + HALF, t + 2);
;     WAIT_V(6); BAR; MMA(1, 1, At, B1); BAR;
;     LDB(B0, 1, 0); SCHED; LDA(At, 1, 0); STAGE(SA(0, 1), A, brow + HALF, t + 2);
;     WAIT_L(8); BAR; WAIT_L(0); MMA(0, 0, At, B0); BAR; SCHED;
;     LDB(B1, 1, 1); STAGE(SB(1, 0), Bt, bcol, t + 3);
;     BAR; WAIT_L(0); MMA(0, 1, At, B1); BAR;
;     LDA(At, 1, 1); STAGE(SA(1, 0), A, brow, t + 3);
	v_readfirstlane_b32 s17, v157
	v_add_u32_e32 v171, 0x2000, v157
	v_lshl_add_u64 v[172:173], v[216:217], 0, s[36:37]
	s_mov_b32 m0, s17
	v_readfirstlane_b32 s17, v171
	global_load_lds_dwordx4 v[172:173], off
	v_lshl_add_u64 v[172:173], v[218:219], 0, s[36:37]
	s_mov_b32 m0, s17
	s_nop 0
	global_load_lds_dwordx4 v[172:173], off
	s_waitcnt vmcnt(6)
	s_barrier
	s_setprio 1
	v_mfma_f32_16x16x32_bf16 v[28:31], v[188:191], v[234:237], v[28:31]
	v_mfma_f32_16x16x32_bf16 v[24:27], v[188:191], v[242:245], v[24:27]
	v_mfma_f32_16x16x32_bf16 v[20:23], v[196:199], v[234:237], v[20:23]
	v_mfma_f32_16x16x32_bf16 v[16:19], v[196:199], v[242:245], v[16:19]
	v_mfma_f32_16x16x32_bf16 v[12:15], v[204:207], v[234:237], v[12:15]
	v_mfma_f32_16x16x32_bf16 v[8:11], v[204:207], v[242:245], v[8:11]
	v_mfma_f32_16x16x32_bf16 v[4:7], v[226:229], v[234:237], v[4:7]
	v_mfma_f32_16x16x32_bf16 v[0:3], v[226:229], v[242:245], v[0:3]
	v_mfma_f32_16x16x32_bf16 v[28:31], v[192:195], v[238:241], v[28:31]
	v_mfma_f32_16x16x32_bf16 v[24:27], v[192:195], v[246:249], v[24:27]
	v_mfma_f32_16x16x32_bf16 v[20:23], v[200:203], v[238:241], v[20:23]
	v_mfma_f32_16x16x32_bf16 v[16:19], v[200:203], v[246:249], v[16:19]
	v_mfma_f32_16x16x32_bf16 v[12:15], v[222:225], v[238:241], v[12:15]
	v_mfma_f32_16x16x32_bf16 v[8:11], v[222:225], v[246:249], v[8:11]
	v_mfma_f32_16x16x32_bf16 v[4:7], v[230:233], v[238:241], v[4:7]
	v_mfma_f32_16x16x32_bf16 v[0:3], v[230:233], v[246:249], v[0:3]
	s_setprio 0
	s_barrier
	ds_read_b128 v[172:175], v156
	ds_read_b128 v[176:179], v156 offset:1024
	ds_read_b128 v[180:183], v156 offset:2048
	ds_read_b128 v[184:187], v156 offset:3072
	v_readfirstlane_b32 s17, v158
	v_lshl_add_u64 v[234:235], v[208:209], 0, s[34:35]
	s_mov_b32 m0, s17
	v_readfirstlane_b32 s17, v159
	ds_read_b128 v[188:191], v152 offset:32768
	ds_read_b128 v[192:195], v152 offset:33792
	ds_read_b128 v[196:199], v151 offset:32768
	ds_read_b128 v[200:203], v151 offset:33792
	ds_read_b128 v[204:207], v150 offset:32768
	ds_read_b128 v[222:225], v150 offset:33792
	ds_read_b128 v[226:229], v149 offset:32768
	ds_read_b128 v[230:233], v149 offset:33792
	global_load_lds_dwordx4 v[234:235], off
	v_lshl_add_u64 v[234:235], v[212:213], 0, s[34:35]
	s_mov_b32 m0, s17
	s_nop 0
	global_load_lds_dwordx4 v[234:235], off
	s_waitcnt lgkmcnt(8)
	s_barrier
	s_waitcnt lgkmcnt(0)
	s_setprio 1
	s_waitcnt lgkmcnt(0)
	v_mfma_f32_16x16x32_bf16 v[126:129], v[188:191], v[172:175], v[126:129]
	v_mfma_f32_16x16x32_bf16 v[122:125], v[188:191], v[180:183], v[122:125]
	v_mfma_f32_16x16x32_bf16 v[118:121], v[196:199], v[172:175], v[118:121]
	v_mfma_f32_16x16x32_bf16 v[114:117], v[196:199], v[180:183], v[114:117]
	v_mfma_f32_16x16x32_bf16 v[110:113], v[204:207], v[172:175], v[110:113]
	v_mfma_f32_16x16x32_bf16 v[106:109], v[204:207], v[180:183], v[106:109]
	v_mfma_f32_16x16x32_bf16 v[102:105], v[226:229], v[172:175], v[102:105]
	v_mfma_f32_16x16x32_bf16 v[98:101], v[226:229], v[180:183], v[98:101]
	v_mfma_f32_16x16x32_bf16 v[126:129], v[192:195], v[176:179], v[126:129]
	v_mfma_f32_16x16x32_bf16 v[122:125], v[192:195], v[184:187], v[122:125]
	v_mfma_f32_16x16x32_bf16 v[118:121], v[200:203], v[176:179], v[118:121]
	v_mfma_f32_16x16x32_bf16 v[114:117], v[200:203], v[184:187], v[114:117]
	v_mfma_f32_16x16x32_bf16 v[110:113], v[222:225], v[176:179], v[110:113]
	v_mfma_f32_16x16x32_bf16 v[106:109], v[222:225], v[184:187], v[106:109]
	v_mfma_f32_16x16x32_bf16 v[102:105], v[230:233], v[176:179], v[102:105]
	v_mfma_f32_16x16x32_bf16 v[98:101], v[230:233], v[184:187], v[98:101]
	s_setprio 0
	s_barrier
	v_readfirstlane_b32 s17, v160
	v_lshl_add_u64 v[250:251], v[216:217], 0, s[24:25]
	s_mov_b32 m0, s17
	v_readfirstlane_b32 s17, v161
	ds_read_b128 v[234:237], v153
	ds_read_b128 v[238:241], v153 offset:1024
	ds_read_b128 v[242:245], v153 offset:2048
	ds_read_b128 v[246:249], v153 offset:3072
	global_load_lds_dwordx4 v[250:251], off
	v_lshl_add_u64 v[250:251], v[218:219], 0, s[24:25]
	s_mov_b32 m0, s17
	s_nop 0
	global_load_lds_dwordx4 v[250:251], off
	s_barrier
	s_waitcnt lgkmcnt(0)
	s_setprio 1
	s_waitcnt lgkmcnt(0)
	v_mfma_f32_16x16x32_bf16 v[92:95], v[188:191], v[234:237], v[92:95]
	v_mfma_f32_16x16x32_bf16 v[88:91], v[188:191], v[242:245], v[88:91]
	v_mfma_f32_16x16x32_bf16 v[84:87], v[196:199], v[234:237], v[84:87]
	v_mfma_f32_16x16x32_bf16 v[80:83], v[196:199], v[242:245], v[80:83]
	v_mfma_f32_16x16x32_bf16 v[76:79], v[204:207], v[234:237], v[76:79]
	v_mfma_f32_16x16x32_bf16 v[72:75], v[204:207], v[242:245], v[72:75]
	v_mfma_f32_16x16x32_bf16 v[68:71], v[226:229], v[234:237], v[68:71]
	v_mfma_f32_16x16x32_bf16 v[64:67], v[226:229], v[242:245], v[64:67]
	v_mfma_f32_16x16x32_bf16 v[92:95], v[192:195], v[238:241], v[92:95]
	v_mfma_f32_16x16x32_bf16 v[88:91], v[192:195], v[246:249], v[88:91]
	v_mfma_f32_16x16x32_bf16 v[84:87], v[200:203], v[238:241], v[84:87]
	v_mfma_f32_16x16x32_bf16 v[80:83], v[200:203], v[246:249], v[80:83]
	v_mfma_f32_16x16x32_bf16 v[76:79], v[222:225], v[238:241], v[76:79]
	v_mfma_f32_16x16x32_bf16 v[72:75], v[222:225], v[246:249], v[72:75]
	v_mfma_f32_16x16x32_bf16 v[68:71], v[230:233], v[238:241], v[68:71]
	v_mfma_f32_16x16x32_bf16 v[64:67], v[230:233], v[246:249], v[64:67]
	s_setprio 0
	v_readfirstlane_b32 s17, v162
	v_lshl_add_u64 v[208:209], v[208:209], 0, s[22:23]
	s_mov_b32 m0, s17
	v_readfirstlane_b32 s17, v165
	s_barrier
	ds_read_b128 v[188:191], v152 offset:49152
	ds_read_b128 v[192:195], v152 offset:50176
	ds_read_b128 v[196:199], v151 offset:49152
	ds_read_b128 v[200:203], v151 offset:50176
	ds_read_b128 v[204:207], v150 offset:49152
	ds_read_b128 v[222:225], v150 offset:50176
	ds_read_b128 v[226:229], v149 offset:49152
	ds_read_b128 v[230:233], v149 offset:50176
	global_load_lds_dwordx4 v[208:209], off
	v_lshl_add_u64 v[208:209], v[212:213], 0, s[22:23]
	s_mov_b32 m0, s17
	s_nop 0
	global_load_lds_dwordx4 v[208:209], off
	s_barrier
; #define WAIT_V(n) asm volatile("s_waitcnt vmcnt(" #n ")" ::: "memory")
; #define WAIT_L(n) asm volatile("s_waitcnt lgkmcnt(" #n ")" ::: "memory")
; #define BAR __builtin_amdgcn_s_barrier()
; #define SCHED __builtin_amdgcn_sched_barrier(0)
; template <int K>
; __device__ __forceinline__ void gemm_mainloop(const bf16* __restrict__ A, const bf16* __restrict__ Bt, int brow, int bcol,
;                                               f32x4 (&acc)[2][2][4][2], const int tidx) {
;     ...
;     BAR; WAIT_L(0); MMA(1, 0, At, B0); BAR; SCHED;
;     STAGE(SB(1, 1), Bt, bcol + HALF, t + 3);
;     WAIT_V(6); BAR; MMA(1, 1, At, B1); BAR;
;   }
;   { LDB(B0, 0, 0); LDA(At, 0, 0); STAGE(SA(1, 1), A, brow + HALF, nt - 1);
;     BAR; WAIT_L(0); MMA(0, 0, At, B0); BAR;
;     LDB(B1, 0, 1); BAR; WAIT_L(0); MMA(0, 1, At, B1); BAR;
	s_waitcnt lgkmcnt(0)
	s_setprio 1
	s_waitcnt lgkmcnt(0)
	v_mfma_f32_16x16x32_bf16 v[60:63], v[188:191], v[172:175], v[60:63]
	v_mfma_f32_16x16x32_bf16 v[56:59], v[188:191], v[180:183], v[56:59]
	v_mfma_f32_16x16x32_bf16 v[52:55], v[196:199], v[172:175], v[52:55]
	v_mfma_f32_16x16x32_bf16 v[48:51], v[196:199], v[180:183], v[48:51]
	v_mfma_f32_16x16x32_bf16 v[44:47], v[204:207], v[172:175], v[44:47]
	v_mfma_f32_16x16x32_bf16 v[40:43], v[204:207], v[180:183], v[40:43]
	v_mfma_f32_16x16x32_bf16 v[36:39], v[226:229], v[172:175], v[36:39]
	v_mfma_f32_16x16x32_bf16 v[32:35], v[226:229], v[180:183], v[32:35]
	v_mfma_f32_16x16x32_bf16 v[60:63], v[192:195], v[176:179], v[60:63]
	v_mfma_f32_16x16x32_bf16 v[56:59], v[192:195], v[184:187], v[56:59]
	v_mfma_f32_16x16x32_bf16 v[52:55], v[200:203], v[176:179], v[52:55]
	v_mfma_f32_16x16x32_bf16 v[48:51], v[200:203], v[184:187], v[48:51]
	v_mfma_f32_16x16x32_bf16 v[44:47], v[222:225], v[176:179], v[44:47]
	v_mfma_f32_16x16x32_bf16 v[40:43], v[222:225], v[184:187], v[40:43]
	v_mfma_f32_16x16x32_bf16 v[36:39], v[230:233], v[176:179], v[36:39]
	v_mfma_f32_16x16x32_bf16 v[32:35], v[230:233], v[184:187], v[32:35]
	s_setprio 0
	s_barrier
	v_readfirstlane_b32 s17, v166
	v_lshl_add_u64 v[172:173], v[216:217], 0, s[20:21]
	s_mov_b32 m0, s17
	v_readfirstlane_b32 s17, v167
	global_load_lds_dwordx4 v[172:173], off
	v_lshl_add_u64 v[172:173], v[218:219], 0, s[20:21]
	s_mov_b32 m0, s17
	s_nop 0
	global_load_lds_dwordx4 v[172:173], off
	s_waitcnt vmcnt(6)
	s_barrier
	s_setprio 1
	v_mfma_f32_16x16x32_bf16 v[28:31], v[188:191], v[234:237], v[28:31]
	v_mfma_f32_16x16x32_bf16 v[24:27], v[188:191], v[242:245], v[24:27]
	v_mfma_f32_16x16x32_bf16 v[20:23], v[196:199], v[234:237], v[20:23]
	v_mfma_f32_16x16x32_bf16 v[16:19], v[196:199], v[242:245], v[16:19]
	v_mfma_f32_16x16x32_bf16 v[12:15], v[204:207], v[234:237], v[12:15]
	v_mfma_f32_16x16x32_bf16 v[8:11], v[204:207], v[242:245], v[8:11]
	v_mfma_f32_16x16x32_bf16 v[4:7], v[226:229], v[234:237], v[4:7]
	v_mfma_f32_16x16x32_bf16 v[0:3], v[226:229], v[242:245], v[0:3]
	v_mfma_f32_16x16x32_bf16 v[28:31], v[192:195], v[238:241], v[28:31]
	v_mfma_f32_16x16x32_bf16 v[24:27], v[192:195], v[246:249], v[24:27]
	v_mfma_f32_16x16x32_bf16 v[20:23], v[200:203], v[238:241], v[20:23]
	v_mfma_f32_16x16x32_bf16 v[16:19], v[200:203], v[246:249], v[16:19]
	v_mfma_f32_16x16x32_bf16 v[12:15], v[222:225], v[238:241], v[12:15]
	v_mfma_f32_16x16x32_bf16 v[8:11], v[222:225], v[246:249], v[8:11]
	v_mfma_f32_16x16x32_bf16 v[4:7], v[230:233], v[238:241], v[4:7]
	v_mfma_f32_16x16x32_bf16 v[0:3], v[230:233], v[246:249], v[0:3]
	s_setprio 0
	s_add_i32 s15, s15, 2
	v_lshl_add_u64 v[138:139], v[138:139], 0, s[94:95]
	v_lshl_add_u64 v[140:141], v[140:141], 0, s[94:95]
	v_lshl_add_u64 v[142:143], v[142:143], 0, s[94:95]
	s_cmp_lt_u32 s15, 60
	v_lshl_add_u64 v[144:145], v[144:145], 0, s[94:95]
	s_cbranch_scc1 .LBB0_42
	s_barrier
	s_add_u32 s18, s18, 0x1f80
	s_addc_u32 s19, s19, 0
	v_lshl_add_u64 v[132:133], s[18:19], 0, v[132:133]
	v_readfirstlane_b32 s15, v169
	v_lshl_add_u64 v[130:131], v[130:131], 1, v[132:133]
	s_mov_b32 m0, s15
	ds_read_b128 v[138:141], v168
	ds_read_b128 v[142:145], v168 offset:1024
	ds_read_b128 v[158:161], v168 offset:2048
	ds_read_b128 v[172:175], v168 offset:3072
	ds_read_b128 v[176:179], v152
	ds_read_b128 v[180:183], v152 offset:1024
	ds_read_b128 v[184:187], v151
	ds_read_b128 v[188:191], v151 offset:1024
	ds_read_b128 v[192:195], v150
	ds_read_b128 v[196:199], v150 offset:1024
	ds_read_b128 v[200:203], v149
	ds_read_b128 v[204:207], v149 offset:1024
	global_load_lds_dwordx4 v[130:131], off
	v_lshl_add_u64 v[130:131], s[18:19], 0, v[136:137]
	v_readfirstlane_b32 s15, v170
	v_lshl_add_u64 v[130:131], v[134:135], 1, v[130:131]
	s_mov_b32 m0, s15
	s_nop 0
	global_load_lds_dwordx4 v[130:131], off
	s_barrier
	s_waitcnt lgkmcnt(0)
	s_setprio 1
	s_waitcnt lgkmcnt(0)
	v_mfma_f32_16x16x32_bf16 v[126:129], v[176:179], v[138:141], v[126:129]
	v_mfma_f32_16x16x32_bf16 v[122:125], v[176:179], v[158:161], v[122:125]
	v_mfma_f32_16x16x32_bf16 v[118:121], v[184:187], v[138:141], v[118:121]
	v_mfma_f32_16x16x32_bf16 v[114:117], v[184:187], v[158:161], v[114:117]
	v_mfma_f32_16x16x32_bf16 v[110:113], v[192:195], v[138:141], v[110:113]
	v_mfma_f32_16x16x32_bf16 v[106:109], v[192:195], v[158:161], v[106:109]
	v_mfma_f32_16x16x32_bf16 v[102:105], v[200:203], v[138:141], v[102:105]
	v_mfma_f32_16x16x32_bf16 v[98:101], v[200:203], v[158:161], v[98:101]
	v_mfma_f32_16x16x32_bf16 v[126:129], v[180:183], v[142:145], v[126:129]
	v_mfma_f32_16x16x32_bf16 v[122:125], v[180:183], v[172:175], v[122:125]
	v_mfma_f32_16x16x32_bf16 v[118:121], v[188:191], v[142:145], v[118:121]
	v_mfma_f32_16x16x32_bf16 v[114:117], v[188:191], v[172:175], v[114:117]
	v_mfma_f32_16x16x32_bf16 v[110:113], v[196:199], v[142:145], v[110:113]
	v_mfma_f32_16x16x32_bf16 v[106:109], v[196:199], v[172:175], v[106:109]
	v_mfma_f32_16x16x32_bf16 v[102:105], v[204:207], v[142:145], v[102:105]
	v_mfma_f32_16x16x32_bf16 v[98:101], v[204:207], v[172:175], v[98:101]
	s_setprio 0
	s_barrier
	ds_read_b128 v[130:133], v164
	ds_read_b128 v[134:137], v164 offset:1024
	ds_read_b128 v[166:169], v164 offset:2048
	ds_read_b128 v[222:225], v164 offset:3072
	s_barrier
; #define WAIT_V(n) asm volatile("s_waitcnt vmcnt(" #n ")" ::: "memory")
; #define WAIT_L(n) asm volatile("s_waitcnt lgkmcnt(" #n ")" ::: "memory")
; #define BAR __builtin_amdgcn_s_barrier()
; template <int K>
; __device__ __forceinline__ void gemm_mainloop(const bf16* __restrict__ A, const bf16* __restrict__ Bt, int brow, int bcol,
;                                               f32x4 (&acc)[2][2][4][2], const int tidx) {
;     ...
;     LDB(B1, 0, 1); BAR; WAIT_L(0); MMA(0, 1, At, B1); BAR;
;     LDA(At, 0, 1); WAIT_V(4); BAR; WAIT_L(0); MMA(1, 0, At, B0); MMA(1, 1, At, B1); BAR; }
;   { LDB(B0, 1, 0); LDA(At, 1, 0); WAIT_V(2); BAR; WAIT_L(0); MMA(0, 0, At, B0); BAR;
	s_waitcnt lgkmcnt(0)
	s_setprio 1
	s_waitcnt lgkmcnt(0)
	v_mfma_f32_16x16x32_bf16 v[92:95], v[176:179], v[130:133], v[92:95]
	v_mfma_f32_16x16x32_bf16 v[88:91], v[176:179], v[166:169], v[88:91]
	v_mfma_f32_16x16x32_bf16 v[84:87], v[184:187], v[130:133], v[84:87]
	v_mfma_f32_16x16x32_bf16 v[80:83], v[184:187], v[166:169], v[80:83]
	v_mfma_f32_16x16x32_bf16 v[76:79], v[192:195], v[130:133], v[76:79]
	v_mfma_f32_16x16x32_bf16 v[72:75], v[192:195], v[166:169], v[72:75]
	v_mfma_f32_16x16x32_bf16 v[68:71], v[200:203], v[130:133], v[68:71]
	v_mfma_f32_16x16x32_bf16 v[64:67], v[200:203], v[166:169], v[64:67]
	v_mfma_f32_16x16x32_bf16 v[92:95], v[180:183], v[134:137], v[92:95]
	v_mfma_f32_16x16x32_bf16 v[88:91], v[180:183], v[222:225], v[88:91]
	v_mfma_f32_16x16x32_bf16 v[84:87], v[188:191], v[134:137], v[84:87]
	v_mfma_f32_16x16x32_bf16 v[80:83], v[188:191], v[222:225], v[80:83]
	v_mfma_f32_16x16x32_bf16 v[76:79], v[196:199], v[134:137], v[76:79]
	v_mfma_f32_16x16x32_bf16 v[72:75], v[196:199], v[222:225], v[72:75]
	v_mfma_f32_16x16x32_bf16 v[68:71], v[204:207], v[134:137], v[68:71]
	v_mfma_f32_16x16x32_bf16 v[64:67], v[204:207], v[222:225], v[64:67]
	s_setprio 0
	s_barrier
	ds_read_b128 v[176:179], v152 offset:16384
	ds_read_b128 v[180:183], v152 offset:17408
	ds_read_b128 v[184:187], v151 offset:16384
	ds_read_b128 v[188:191], v151 offset:17408
	ds_read_b128 v[192:195], v150 offset:16384
	ds_read_b128 v[196:199], v150 offset:17408
	ds_read_b128 v[200:203], v149 offset:16384
	ds_read_b128 v[204:207], v149 offset:17408
	s_waitcnt vmcnt(4)
	s_barrier
	s_waitcnt lgkmcnt(0)
	s_setprio 1
	s_waitcnt lgkmcnt(0)
	v_mfma_f32_16x16x32_bf16 v[60:63], v[176:179], v[138:141], v[60:63]
	v_mfma_f32_16x16x32_bf16 v[56:59], v[176:179], v[158:161], v[56:59]
	v_mfma_f32_16x16x32_bf16 v[52:55], v[184:187], v[138:141], v[52:55]
	v_mfma_f32_16x16x32_bf16 v[48:51], v[184:187], v[158:161], v[48:51]
	v_mfma_f32_16x16x32_bf16 v[44:47], v[192:195], v[138:141], v[44:47]
	v_mfma_f32_16x16x32_bf16 v[40:43], v[192:195], v[158:161], v[40:43]
	v_mfma_f32_16x16x32_bf16 v[36:39], v[200:203], v[138:141], v[36:39]
	v_mfma_f32_16x16x32_bf16 v[32:35], v[200:203], v[158:161], v[32:35]
	v_mfma_f32_16x16x32_bf16 v[60:63], v[180:183], v[142:145], v[60:63]
	v_mfma_f32_16x16x32_bf16 v[56:59], v[180:183], v[172:175], v[56:59]
	v_mfma_f32_16x16x32_bf16 v[52:55], v[188:191], v[142:145], v[52:55]
	v_mfma_f32_16x16x32_bf16 v[48:51], v[188:191], v[172:175], v[48:51]
	v_mfma_f32_16x16x32_bf16 v[44:47], v[196:199], v[142:145], v[44:47]
	v_mfma_f32_16x16x32_bf16 v[40:43], v[196:199], v[172:175], v[40:43]
	v_mfma_f32_16x16x32_bf16 v[36:39], v[204:207], v[142:145], v[36:39]
	v_mfma_f32_16x16x32_bf16 v[32:35], v[204:207], v[172:175], v[32:35]
	s_setprio 0
	s_setprio 1
	v_mfma_f32_16x16x32_bf16 v[28:31], v[176:179], v[130:133], v[28:31]
	v_mfma_f32_16x16x32_bf16 v[24:27], v[176:179], v[166:169], v[24:27]
	v_mfma_f32_16x16x32_bf16 v[20:23], v[184:187], v[130:133], v[20:23]
	v_mfma_f32_16x16x32_bf16 v[16:19], v[184:187], v[166:169], v[16:19]
	v_mfma_f32_16x16x32_bf16 v[12:15], v[192:195], v[130:133], v[12:15]
	v_mfma_f32_16x16x32_bf16 v[8:11], v[192:195], v[166:169], v[8:11]
	v_mfma_f32_16x16x32_bf16 v[4:7], v[200:203], v[130:133], v[4:7]
	v_mfma_f32_16x16x32_bf16 v[0:3], v[200:203], v[166:169], v[0:3]
	v_mfma_f32_16x16x32_bf16 v[28:31], v[180:183], v[134:137], v[28:31]
	v_mfma_f32_16x16x32_bf16 v[24:27], v[180:183], v[222:225], v[24:27]
	v_mfma_f32_16x16x32_bf16 v[20:23], v[188:191], v[134:137], v[20:23]
	v_mfma_f32_16x16x32_bf16 v[16:19], v[188:191], v[222:225], v[16:19]
	v_mfma_f32_16x16x32_bf16 v[12:15], v[196:199], v[134:137], v[12:15]
	v_mfma_f32_16x16x32_bf16 v[8:11], v[196:199], v[222:225], v[8:11]
	v_mfma_f32_16x16x32_bf16 v[4:7], v[204:207], v[134:137], v[4:7]
	v_mfma_f32_16x16x32_bf16 v[0:3], v[204:207], v[222:225], v[0:3]
	s_setprio 0
	s_barrier
	ds_read_b128 v[130:133], v156
	ds_read_b128 v[134:137], v156 offset:1024
	ds_read_b128 v[138:141], v156 offset:2048
	ds_read_b128 v[142:145], v156 offset:3072
	ds_read_b128 v[154:157], v152 offset:32768
	ds_read_b128 v[158:161], v152 offset:33792
	ds_read_b128 v[164:167], v151 offset:32768
	ds_read_b128 v[168:171], v151 offset:33792
	ds_read_b128 v[172:175], v150 offset:32768
	ds_read_b128 v[176:179], v150 offset:33792
	ds_read_b128 v[180:183], v149 offset:32768
	ds_read_b128 v[184:187], v149 offset:33792
	s_waitcnt vmcnt(2)
	s_barrier
; #define WAIT_V(n) asm volatile("s_waitcnt vmcnt(" #n ")" ::: "memory")
; #define WAIT_L(n) asm volatile("s_waitcnt lgkmcnt(" #n ")" ::: "memory")
; #define BAR __builtin_amdgcn_s_barrier()
; template <int K>
; __device__ __forceinline__ void gemm_mainloop(const bf16* __restrict__ A, const bf16* __restrict__ Bt, int brow, int bcol,
;                                               f32x4 (&acc)[2][2][4][2], const int tidx) {
;     ...
;   { LDB(B0, 1, 0); LDA(At, 1, 0); WAIT_V(2); BAR; WAIT_L(0); MMA(0, 0, At, B0); BAR;
;     LDB(B1, 1, 1); WAIT_V(0); BAR; WAIT_L(0); MMA(0, 1, At, B1); BAR;
;     LDA(At, 1, 1); BAR; WAIT_L(0); MMA(1, 0, At, B0); MMA(1, 1, At, B1); BAR; }
;   if (wr == 0) BAR;
	s_waitcnt lgkmcnt(0)
	s_setprio 1
	s_waitcnt lgkmcnt(0)
	v_mfma_f32_16x16x32_bf16 v[126:129], v[154:157], v[130:133], v[126:129]
	v_mfma_f32_16x16x32_bf16 v[122:125], v[154:157], v[138:141], v[122:125]
	v_mfma_f32_16x16x32_bf16 v[118:121], v[164:167], v[130:133], v[118:121]
	v_mfma_f32_16x16x32_bf16 v[114:117], v[164:167], v[138:141], v[114:117]
	v_mfma_f32_16x16x32_bf16 v[110:113], v[172:175], v[130:133], v[110:113]
	v_mfma_f32_16x16x32_bf16 v[106:109], v[172:175], v[138:141], v[106:109]
	v_mfma_f32_16x16x32_bf16 v[102:105], v[180:183], v[130:133], v[102:105]
	v_mfma_f32_16x16x32_bf16 v[98:101], v[180:183], v[138:141], v[98:101]
	v_mfma_f32_16x16x32_bf16 v[126:129], v[158:161], v[134:137], v[126:129]
	v_mfma_f32_16x16x32_bf16 v[122:125], v[158:161], v[142:145], v[122:125]
	v_mfma_f32_16x16x32_bf16 v[118:121], v[168:171], v[134:137], v[118:121]
	v_mfma_f32_16x16x32_bf16 v[114:117], v[168:171], v[142:145], v[114:117]
	v_mfma_f32_16x16x32_bf16 v[110:113], v[176:179], v[134:137], v[110:113]
	v_mfma_f32_16x16x32_bf16 v[106:109], v[176:179], v[142:145], v[106:109]
	v_mfma_f32_16x16x32_bf16 v[102:105], v[184:187], v[134:137], v[102:105]
	v_mfma_f32_16x16x32_bf16 v[98:101], v[184:187], v[142:145], v[98:101]
	s_setprio 0
	s_barrier
	ds_read_b128 v[188:191], v153
	ds_read_b128 v[192:195], v153 offset:1024
	ds_read_b128 v[196:199], v153 offset:2048
	ds_read_b128 v[200:203], v153 offset:3072
	s_waitcnt vmcnt(0)
	s_barrier
	s_waitcnt lgkmcnt(0)
	s_setprio 1
	s_waitcnt lgkmcnt(0)
	v_mfma_f32_16x16x32_bf16 v[92:95], v[154:157], v[188:191], v[92:95]
	v_mfma_f32_16x16x32_bf16 v[88:91], v[154:157], v[196:199], v[88:91]
	v_mfma_f32_16x16x32_bf16 v[84:87], v[164:167], v[188:191], v[84:87]
	v_mfma_f32_16x16x32_bf16 v[80:83], v[164:167], v[196:199], v[80:83]
	v_mfma_f32_16x16x32_bf16 v[76:79], v[172:175], v[188:191], v[76:79]
	v_mfma_f32_16x16x32_bf16 v[72:75], v[172:175], v[196:199], v[72:75]
	v_mfma_f32_16x16x32_bf16 v[68:71], v[180:183], v[188:191], v[68:71]
	v_mfma_f32_16x16x32_bf16 v[64:67], v[180:183], v[196:199], v[64:67]
	v_mfma_f32_16x16x32_bf16 v[92:95], v[158:161], v[192:195], v[92:95]
	v_mfma_f32_16x16x32_bf16 v[88:91], v[158:161], v[200:203], v[88:91]
	v_mfma_f32_16x16x32_bf16 v[84:87], v[168:171], v[192:195], v[84:87]
	v_mfma_f32_16x16x32_bf16 v[80:83], v[168:171], v[200:203], v[80:83]
	v_mfma_f32_16x16x32_bf16 v[76:79], v[176:179], v[192:195], v[76:79]
	v_mfma_f32_16x16x32_bf16 v[72:75], v[176:179], v[200:203], v[72:75]
	v_mfma_f32_16x16x32_bf16 v[68:71], v[184:187], v[192:195], v[68:71]
	v_mfma_f32_16x16x32_bf16 v[64:67], v[184:187], v[200:203], v[64:67]
	s_setprio 0
	s_barrier
	ds_read_b128 v[154:157], v152 offset:49152
	ds_read_b128 v[158:161], v152 offset:50176
	ds_read_b128 v[164:167], v151 offset:49152
	ds_read_b128 v[168:171], v151 offset:50176
	ds_read_b128 v[172:175], v150 offset:49152
	ds_read_b128 v[150:153], v150 offset:50176
	ds_read_b128 v[176:179], v149 offset:49152
	ds_read_b128 v[180:183], v149 offset:50176
	s_barrier
	s_waitcnt lgkmcnt(0)
	s_setprio 1
	s_waitcnt lgkmcnt(0)
	v_mfma_f32_16x16x32_bf16 v[60:63], v[154:157], v[130:133], v[60:63]
	v_mfma_f32_16x16x32_bf16 v[56:59], v[154:157], v[138:141], v[56:59]
	v_mfma_f32_16x16x32_bf16 v[52:55], v[164:167], v[130:133], v[52:55]
	v_mfma_f32_16x16x32_bf16 v[48:51], v[164:167], v[138:141], v[48:51]
	v_mfma_f32_16x16x32_bf16 v[44:47], v[172:175], v[130:133], v[44:47]
	v_mfma_f32_16x16x32_bf16 v[40:43], v[172:175], v[138:141], v[40:43]
	v_mfma_f32_16x16x32_bf16 v[36:39], v[176:179], v[130:133], v[36:39]
	v_mfma_f32_16x16x32_bf16 v[32:35], v[176:179], v[138:141], v[32:35]
	v_mfma_f32_16x16x32_bf16 v[60:63], v[158:161], v[134:137], v[60:63]
	v_mfma_f32_16x16x32_bf16 v[56:59], v[158:161], v[142:145], v[56:59]
	v_mfma_f32_16x16x32_bf16 v[52:55], v[168:171], v[134:137], v[52:55]
	v_mfma_f32_16x16x32_bf16 v[48:51], v[168:171], v[142:145], v[48:51]
	v_mfma_f32_16x16x32_bf16 v[44:47], v[150:153], v[134:137], v[44:47]
	v_mfma_f32_16x16x32_bf16 v[40:43], v[150:153], v[142:145], v[40:43]
	v_mfma_f32_16x16x32_bf16 v[36:39], v[180:183], v[134:137], v[36:39]
	v_mfma_f32_16x16x32_bf16 v[32:35], v[180:183], v[142:145], v[32:35]
	s_setprio 0
	s_setprio 1
	v_mfma_f32_16x16x32_bf16 v[28:31], v[154:157], v[188:191], v[28:31]
	v_mfma_f32_16x16x32_bf16 v[24:27], v[154:157], v[196:199], v[24:27]
	v_mfma_f32_16x16x32_bf16 v[20:23], v[164:167], v[188:191], v[20:23]
	v_mfma_f32_16x16x32_bf16 v[16:19], v[164:167], v[196:199], v[16:19]
	v_mfma_f32_16x16x32_bf16 v[12:15], v[172:175], v[188:191], v[12:15]
	v_mfma_f32_16x16x32_bf16 v[8:11], v[172:175], v[196:199], v[8:11]
	v_mfma_f32_16x16x32_bf16 v[4:7], v[176:179], v[188:191], v[4:7]
	v_mfma_f32_16x16x32_bf16 v[0:3], v[176:179], v[196:199], v[0:3]
	v_mfma_f32_16x16x32_bf16 v[28:31], v[158:161], v[192:195], v[28:31]
	v_mfma_f32_16x16x32_bf16 v[24:27], v[158:161], v[200:203], v[24:27]
	v_mfma_f32_16x16x32_bf16 v[20:23], v[168:171], v[192:195], v[20:23]
	v_mfma_f32_16x16x32_bf16 v[16:19], v[168:171], v[200:203], v[16:19]
	v_mfma_f32_16x16x32_bf16 v[12:15], v[150:153], v[192:195], v[12:15]
	v_mfma_f32_16x16x32_bf16 v[8:11], v[150:153], v[200:203], v[8:11]
	v_mfma_f32_16x16x32_bf16 v[4:7], v[180:183], v[192:195], v[4:7]
	v_mfma_f32_16x16x32_bf16 v[0:3], v[180:183], v[200:203], v[0:3]
	s_setprio 0
	v_cmp_gt_u32_e32 vcc, s50, v97
	s_barrier
	s_and_saveexec_b64 s[18:19], vcc
	s_cbranch_execz .LBB0_34
	s_barrier
	s_branch .LBB0_34

; #define WAIT_V(n) asm volatile("s_waitcnt vmcnt(" #n ")" ::: "memory")
; #define WAIT_L(n) asm volatile("s_waitcnt lgkmcnt(" #n ")" ::: "memory")
; #define BAR __builtin_amdgcn_s_barrier()
; #define SCHED __builtin_amdgcn_sched_barrier(0)
; template <int K>
; __device__ __forceinline__ void gemm_mainloop(const bf16* __restrict__ A, const bf16* __restrict__ Bt, int brow, int bcol,
;                                               f32x4 (&acc)[2][2][4][2], const int tidx) {
;     ...
;   for (int t = 0; t < nt - 2; t += 2) {
;     LDB(B0, 0, 0); SCHED; LDA(At, 0, 0); STAGE(SA(1, 1), A, brow + HALF, t + 1);
;     WAIT_L(8); BAR; WAIT_L(0); MMA(0, 0, At, B0); BAR; SCHED;
;     LDB(B1, 0, 1); STAGE(SB(0, 0), Bt, bcol, t + 2);
;     BAR; WAIT_L(0); MMA(0, 1, At, B1); BAR;
;     LDA(At, 0, 1); STAGE(SA(0, 0), A, brow, t + 2);
;     BAR; WAIT_L(0); MMA(1, 0, At, B0); BAR; SCHED;
;     STAGE(SB(0, 1), Bt, bcol + HALF, t + 2);
;     WAIT_V(6); BAR; MMA(1, 1, At, B1); BAR;
.LBB0_64:
	s_barrier
	ds_read_b128 v[168:171], v161
	ds_read_b128 v[172:175], v161 offset:1024
	ds_read_b128 v[176:179], v161 offset:2048
	ds_read_b128 v[180:183], v161 offset:3072
	v_add_u32_e32 v162, 0xc000, v143
	v_lshl_add_u64 v[208:209], s[86:87], 0, v[138:139]
	v_readfirstlane_b32 s12, v162
	v_lshl_add_u64 v[212:213], v[208:209], 0, s[14:15]
	s_mov_b32 m0, s12
	v_add_u32_e32 v165, 0xe000, v143
	ds_read_b128 v[184:187], v149
	ds_read_b128 v[188:191], v149 offset:1024
	ds_read_b128 v[192:195], v148
	ds_read_b128 v[196:199], v148 offset:1024
	ds_read_b128 v[200:203], v147
	ds_read_b128 v[204:207], v147 offset:1024
	ds_read_b128 v[222:225], v146
	ds_read_b128 v[226:229], v146 offset:1024
	global_load_lds_dwordx4 v[212:213], off
	v_lshl_add_u64 v[212:213], s[86:87], 0, v[140:141]
	v_readfirstlane_b32 s12, v165
	v_lshl_add_u64 v[216:217], v[212:213], 0, s[14:15]
	s_mov_b32 m0, s12
	s_nop 0
	global_load_lds_dwordx4 v[216:217], off
	s_waitcnt lgkmcnt(8)
	s_barrier
	s_waitcnt lgkmcnt(0)
	s_setprio 1
	s_waitcnt lgkmcnt(0)
	v_mfma_f32_16x16x32_bf16 v[126:129], v[184:187], v[168:171], v[126:129]
	v_mfma_f32_16x16x32_bf16 v[122:125], v[184:187], v[176:179], v[122:125]
	v_mfma_f32_16x16x32_bf16 v[118:121], v[192:195], v[168:171], v[118:121]
	v_mfma_f32_16x16x32_bf16 v[114:117], v[192:195], v[176:179], v[114:117]
	v_mfma_f32_16x16x32_bf16 v[110:113], v[200:203], v[168:171], v[110:113]
	v_mfma_f32_16x16x32_bf16 v[106:109], v[200:203], v[176:179], v[106:109]
	v_mfma_f32_16x16x32_bf16 v[102:105], v[222:225], v[168:171], v[102:105]
	v_mfma_f32_16x16x32_bf16 v[98:101], v[222:225], v[176:179], v[98:101]
	v_mfma_f32_16x16x32_bf16 v[126:129], v[188:191], v[172:175], v[126:129]
	v_mfma_f32_16x16x32_bf16 v[122:125], v[188:191], v[180:183], v[122:125]
	v_mfma_f32_16x16x32_bf16 v[118:121], v[196:199], v[172:175], v[118:121]
	v_mfma_f32_16x16x32_bf16 v[114:117], v[196:199], v[180:183], v[114:117]
	v_mfma_f32_16x16x32_bf16 v[110:113], v[204:207], v[172:175], v[110:113]
	v_mfma_f32_16x16x32_bf16 v[106:109], v[204:207], v[180:183], v[106:109]
	v_mfma_f32_16x16x32_bf16 v[102:105], v[226:229], v[172:175], v[102:105]
	v_mfma_f32_16x16x32_bf16 v[98:101], v[226:229], v[180:183], v[98:101]
	s_setprio 0
	s_barrier
	v_lshl_add_u64 v[216:217], s[86:87], 0, v[134:135]
	v_readfirstlane_b32 s12, v142
	v_lshl_add_u64 v[218:219], v[216:217], 0, s[16:17]
	s_mov_b32 m0, s12
	v_add_u32_e32 v167, 0x2000, v142
	ds_read_b128 v[230:233], v159
	ds_read_b128 v[234:237], v159 offset:1024
	ds_read_b128 v[238:241], v159 offset:2048
	ds_read_b128 v[242:245], v159 offset:3072
	global_load_lds_dwordx4 v[218:219], off
	v_lshl_add_u64 v[218:219], s[86:87], 0, v[136:137]
	v_readfirstlane_b32 s12, v167
	v_lshl_add_u64 v[246:247], v[218:219], 0, s[16:17]
	s_mov_b32 m0, s12
	s_nop 0
	global_load_lds_dwordx4 v[246:247], off
	s_barrier
	s_waitcnt lgkmcnt(0)
	s_setprio 1
	s_waitcnt lgkmcnt(0)
	v_mfma_f32_16x16x32_bf16 v[92:95], v[184:187], v[230:233], v[92:95]
	v_mfma_f32_16x16x32_bf16 v[88:91], v[184:187], v[238:241], v[88:91]
	v_mfma_f32_16x16x32_bf16 v[84:87], v[192:195], v[230:233], v[84:87]
	v_mfma_f32_16x16x32_bf16 v[80:83], v[192:195], v[238:241], v[80:83]
	v_mfma_f32_16x16x32_bf16 v[76:79], v[200:203], v[230:233], v[76:79]
	v_mfma_f32_16x16x32_bf16 v[72:75], v[200:203], v[238:241], v[72:75]
	v_mfma_f32_16x16x32_bf16 v[68:71], v[222:225], v[230:233], v[68:71]
	v_mfma_f32_16x16x32_bf16 v[64:67], v[222:225], v[238:241], v[64:67]
	v_mfma_f32_16x16x32_bf16 v[92:95], v[188:191], v[234:237], v[92:95]
	v_mfma_f32_16x16x32_bf16 v[88:91], v[188:191], v[242:245], v[88:91]
	v_mfma_f32_16x16x32_bf16 v[84:87], v[196:199], v[234:237], v[84:87]
	v_mfma_f32_16x16x32_bf16 v[80:83], v[196:199], v[242:245], v[80:83]
	v_mfma_f32_16x16x32_bf16 v[76:79], v[204:207], v[234:237], v[76:79]
	v_mfma_f32_16x16x32_bf16 v[72:75], v[204:207], v[242:245], v[72:75]
	v_mfma_f32_16x16x32_bf16 v[68:71], v[226:229], v[234:237], v[68:71]
	v_mfma_f32_16x16x32_bf16 v[64:67], v[226:229], v[242:245], v[64:67]
	s_setprio 0
	v_readfirstlane_b32 s12, v143
	v_lshl_add_u64 v[246:247], v[208:209], 0, s[28:29]
	s_mov_b32 m0, s12
	v_readfirstlane_b32 s12, v144
	s_barrier
	ds_read_b128 v[184:187], v149 offset:16384
	ds_read_b128 v[188:191], v149 offset:17408
	ds_read_b128 v[192:195], v148 offset:16384
	ds_read_b128 v[196:199], v148 offset:17408
	ds_read_b128 v[200:203], v147 offset:16384
	ds_read_b128 v[204:207], v147 offset:17408
	ds_read_b128 v[222:225], v146 offset:16384
	ds_read_b128 v[226:229], v146 offset:17408
	global_load_lds_dwordx4 v[246:247], off
	v_lshl_add_u64 v[246:247], v[212:213], 0, s[28:29]
	s_mov_b32 m0, s12
	s_nop 0
	global_load_lds_dwordx4 v[246:247], off
	s_barrier
	s_waitcnt lgkmcnt(0)
	s_setprio 1
	s_waitcnt lgkmcnt(0)
	v_mfma_f32_16x16x32_bf16 v[60:63], v[184:187], v[168:171], v[60:63]
	v_mfma_f32_16x16x32_bf16 v[56:59], v[184:187], v[176:179], v[56:59]
	v_mfma_f32_16x16x32_bf16 v[52:55], v[192:195], v[168:171], v[52:55]
	v_mfma_f32_16x16x32_bf16 v[48:51], v[192:195], v[176:179], v[48:51]
	v_mfma_f32_16x16x32_bf16 v[44:47], v[200:203], v[168:171], v[44:47]
	v_mfma_f32_16x16x32_bf16 v[40:43], v[200:203], v[176:179], v[40:43]
	v_mfma_f32_16x16x32_bf16 v[36:39], v[222:225], v[168:171], v[36:39]
	v_mfma_f32_16x16x32_bf16 v[32:35], v[222:225], v[176:179], v[32:35]
	v_mfma_f32_16x16x32_bf16 v[60:63], v[188:191], v[172:175], v[60:63]
	v_mfma_f32_16x16x32_bf16 v[56:59], v[188:191], v[180:183], v[56:59]
	v_mfma_f32_16x16x32_bf16 v[52:55], v[196:199], v[172:175], v[52:55]
	v_mfma_f32_16x16x32_bf16 v[48:51], v[196:199], v[180:183], v[48:51]
	v_mfma_f32_16x16x32_bf16 v[44:47], v[204:207], v[172:175], v[44:47]
	v_mfma_f32_16x16x32_bf16 v[40:43], v[204:207], v[180:183], v[40:43]
	v_mfma_f32_16x16x32_bf16 v[36:39], v[226:229], v[172:175], v[36:39]
	v_mfma_f32_16x16x32_bf16 v[32:35], v[226:229], v[180:183], v[32:35]
	s_setprio 0
	s_barrier
; #define WAIT_V(n) asm volatile("s_waitcnt vmcnt(" #n ")" ::: "memory")
; #define WAIT_L(n) asm volatile("s_waitcnt lgkmcnt(" #n ")" ::: "memory")
; #define BAR __builtin_amdgcn_s_barrier()
; #define SCHED __builtin_amdgcn_sched_barrier(0)
; template <int K>
; __device__ __forceinline__ void gemm_mainloop(const bf16* __restrict__ A, const bf16* __restrict__ Bt, int brow, int bcol,
;                                               f32x4 (&acc)[2][2][4][2], const int tidx) {
;     ...
;     STAGE(SB(0, 1), Bt, bcol + HALF, t + 2);
;     WAIT_V(6); BAR; MMA(1, 1, At, B1); BAR;
;     LDB(B0, 1, 0); SCHED; LDA(At, 1, 0); STAGE(SA(0, 1), A, brow + HALF, t + 2);
;     WAIT_L(8); BAR; WAIT_L(0); MMA(0, 0, At, B0); BAR; SCHED;
;     LDB(B1, 1, 1); STAGE(SB(1, 0), Bt, bcol, t + 3);
;     BAR; WAIT_L(0); MMA(0, 1, At, B1); BAR;
;     LDA(At, 1, 1); STAGE(SA(1, 0), A, brow, t + 3);
	v_readfirstlane_b32 s12, v145
	v_add_u32_e32 v167, 0x2000, v145
	v_lshl_add_u64 v[168:169], v[216:217], 0, s[96:97]
	s_mov_b32 m0, s12
	v_readfirstlane_b32 s12, v167
	global_load_lds_dwordx4 v[168:169], off
	v_lshl_add_u64 v[168:169], v[218:219], 0, s[96:97]
	s_mov_b32 m0, s12
	s_nop 0
	global_load_lds_dwordx4 v[168:169], off
	s_waitcnt vmcnt(6)
	s_barrier
	s_setprio 1
	v_mfma_f32_16x16x32_bf16 v[28:31], v[184:187], v[230:233], v[28:31]
	v_mfma_f32_16x16x32_bf16 v[24:27], v[184:187], v[238:241], v[24:27]
	v_mfma_f32_16x16x32_bf16 v[20:23], v[192:195], v[230:233], v[20:23]
	v_mfma_f32_16x16x32_bf16 v[16:19], v[192:195], v[238:241], v[16:19]
	v_mfma_f32_16x16x32_bf16 v[12:15], v[200:203], v[230:233], v[12:15]
	v_mfma_f32_16x16x32_bf16 v[8:11], v[200:203], v[238:241], v[8:11]
	v_mfma_f32_16x16x32_bf16 v[4:7], v[222:225], v[230:233], v[4:7]
	v_mfma_f32_16x16x32_bf16 v[0:3], v[222:225], v[238:241], v[0:3]
	v_mfma_f32_16x16x32_bf16 v[28:31], v[188:191], v[234:237], v[28:31]
	v_mfma_f32_16x16x32_bf16 v[24:27], v[188:191], v[242:245], v[24:27]
	v_mfma_f32_16x16x32_bf16 v[20:23], v[196:199], v[234:237], v[20:23]
	v_mfma_f32_16x16x32_bf16 v[16:19], v[196:199], v[242:245], v[16:19]
	v_mfma_f32_16x16x32_bf16 v[12:15], v[204:207], v[234:237], v[12:15]
	v_mfma_f32_16x16x32_bf16 v[8:11], v[204:207], v[242:245], v[8:11]
	v_mfma_f32_16x16x32_bf16 v[4:7], v[226:229], v[234:237], v[4:7]
	v_mfma_f32_16x16x32_bf16 v[0:3], v[226:229], v[242:245], v[0:3]
	s_setprio 0
	s_barrier
	ds_read_b128 v[168:171], v150
	ds_read_b128 v[172:175], v150 offset:1024
	ds_read_b128 v[176:179], v150 offset:2048
	ds_read_b128 v[180:183], v150 offset:3072
	v_readfirstlane_b32 s12, v151
	v_lshl_add_u64 v[230:231], v[208:209], 0, s[54:55]
	s_mov_b32 m0, s12
	v_readfirstlane_b32 s12, v152
	ds_read_b128 v[184:187], v149 offset:32768
	ds_read_b128 v[188:191], v149 offset:33792
	ds_read_b128 v[192:195], v148 offset:32768
	ds_read_b128 v[196:199], v148 offset:33792
	ds_read_b128 v[200:203], v147 offset:32768
	ds_read_b128 v[204:207], v147 offset:33792
	ds_read_b128 v[222:225], v146 offset:32768
	ds_read_b128 v[226:229], v146 offset:33792
	global_load_lds_dwordx4 v[230:231], off
	v_lshl_add_u64 v[230:231], v[212:213], 0, s[54:55]
	s_mov_b32 m0, s12
	s_nop 0
	global_load_lds_dwordx4 v[230:231], off
	s_waitcnt lgkmcnt(8)
	s_barrier
	s_waitcnt lgkmcnt(0)
	s_setprio 1
	s_waitcnt lgkmcnt(0)
	v_mfma_f32_16x16x32_bf16 v[126:129], v[184:187], v[168:171], v[126:129]
	v_mfma_f32_16x16x32_bf16 v[122:125], v[184:187], v[176:179], v[122:125]
	v_mfma_f32_16x16x32_bf16 v[118:121], v[192:195], v[168:171], v[118:121]
	v_mfma_f32_16x16x32_bf16 v[114:117], v[192:195], v[176:179], v[114:117]
	v_mfma_f32_16x16x32_bf16 v[110:113], v[200:203], v[168:171], v[110:113]
	v_mfma_f32_16x16x32_bf16 v[106:109], v[200:203], v[176:179], v[106:109]
	v_mfma_f32_16x16x32_bf16 v[102:105], v[222:225], v[168:171], v[102:105]
	v_mfma_f32_16x16x32_bf16 v[98:101], v[222:225], v[176:179], v[98:101]
	v_mfma_f32_16x16x32_bf16 v[126:129], v[188:191], v[172:175], v[126:129]
	v_mfma_f32_16x16x32_bf16 v[122:125], v[188:191], v[180:183], v[122:125]
	v_mfma_f32_16x16x32_bf16 v[118:121], v[196:199], v[172:175], v[118:121]
	v_mfma_f32_16x16x32_bf16 v[114:117], v[196:199], v[180:183], v[114:117]
	v_mfma_f32_16x16x32_bf16 v[110:113], v[204:207], v[172:175], v[110:113]
	v_mfma_f32_16x16x32_bf16 v[106:109], v[204:207], v[180:183], v[106:109]
	v_mfma_f32_16x16x32_bf16 v[102:105], v[226:229], v[172:175], v[102:105]
	v_mfma_f32_16x16x32_bf16 v[98:101], v[226:229], v[180:183], v[98:101]
	s_setprio 0
	s_barrier
	v_readfirstlane_b32 s12, v153
	v_lshl_add_u64 v[246:247], v[216:217], 0, s[46:47]
	s_mov_b32 m0, s12
	v_readfirstlane_b32 s12, v155
	ds_read_b128 v[230:233], v154
	ds_read_b128 v[234:237], v154 offset:1024
	ds_read_b128 v[238:241], v154 offset:2048
	ds_read_b128 v[242:245], v154 offset:3072
	global_load_lds_dwordx4 v[246:247], off
	v_lshl_add_u64 v[246:247], v[218:219], 0, s[46:47]
	s_mov_b32 m0, s12
	s_nop 0
	global_load_lds_dwordx4 v[246:247], off
	s_barrier
	s_waitcnt lgkmcnt(0)
	s_setprio 1
	s_waitcnt lgkmcnt(0)
	v_mfma_f32_16x16x32_bf16 v[92:95], v[184:187], v[230:233], v[92:95]
	v_mfma_f32_16x16x32_bf16 v[88:91], v[184:187], v[238:241], v[88:91]
	v_mfma_f32_16x16x32_bf16 v[84:87], v[192:195], v[230:233], v[84:87]
	v_mfma_f32_16x16x32_bf16 v[80:83], v[192:195], v[238:241], v[80:83]
	v_mfma_f32_16x16x32_bf16 v[76:79], v[200:203], v[230:233], v[76:79]
	v_mfma_f32_16x16x32_bf16 v[72:75], v[200:203], v[238:241], v[72:75]
	v_mfma_f32_16x16x32_bf16 v[68:71], v[222:225], v[230:233], v[68:71]
	v_mfma_f32_16x16x32_bf16 v[64:67], v[222:225], v[238:241], v[64:67]
	v_mfma_f32_16x16x32_bf16 v[92:95], v[188:191], v[234:237], v[92:95]
	v_mfma_f32_16x16x32_bf16 v[88:91], v[188:191], v[242:245], v[88:91]
	v_mfma_f32_16x16x32_bf16 v[84:87], v[196:199], v[234:237], v[84:87]
	v_mfma_f32_16x16x32_bf16 v[80:83], v[196:199], v[242:245], v[80:83]
	v_mfma_f32_16x16x32_bf16 v[76:79], v[204:207], v[234:237], v[76:79]
	v_mfma_f32_16x16x32_bf16 v[72:75], v[204:207], v[242:245], v[72:75]
	v_mfma_f32_16x16x32_bf16 v[68:71], v[226:229], v[234:237], v[68:71]
	v_mfma_f32_16x16x32_bf16 v[64:67], v[226:229], v[242:245], v[64:67]
	s_setprio 0
	v_readfirstlane_b32 s12, v156
	v_lshl_add_u64 v[208:209], v[208:209], 0, s[52:53]
	s_mov_b32 m0, s12
	v_readfirstlane_b32 s12, v157
	s_barrier
	ds_read_b128 v[184:187], v149 offset:49152
	ds_read_b128 v[188:191], v149 offset:50176
	ds_read_b128 v[192:195], v148 offset:49152
	ds_read_b128 v[196:199], v148 offset:50176
	ds_read_b128 v[200:203], v147 offset:49152
	ds_read_b128 v[204:207], v147 offset:50176
	ds_read_b128 v[222:225], v146 offset:49152
	ds_read_b128 v[226:229], v146 offset:50176
	global_load_lds_dwordx4 v[208:209], off
	v_lshl_add_u64 v[208:209], v[212:213], 0, s[52:53]
	s_mov_b32 m0, s12
	s_nop 0
	global_load_lds_dwordx4 v[208:209], off
	s_barrier
; #define WAIT_V(n) asm volatile("s_waitcnt vmcnt(" #n ")" ::: "memory")
; #define WAIT_L(n) asm volatile("s_waitcnt lgkmcnt(" #n ")" ::: "memory")
; #define BAR __builtin_amdgcn_s_barrier()
; #define SCHED __builtin_amdgcn_sched_barrier(0)
; template <int K>
; __device__ __forceinline__ void gemm_mainloop(const bf16* __restrict__ A, const bf16* __restrict__ Bt, int brow, int bcol,
;                                               f32x4 (&acc)[2][2][4][2], const int tidx) {
;     ...
;     BAR; WAIT_L(0); MMA(1, 0, At, B0); BAR; SCHED;
;     STAGE(SB(1, 1), Bt, bcol + HALF, t + 3);
;     WAIT_V(6); BAR; MMA(1, 1, At, B1); BAR;
;   }
;   { LDB(B0, 0, 0); LDA(At, 0, 0); STAGE(SA(1, 1), A, brow + HALF, nt - 1);
;     BAR; WAIT_L(0); MMA(0, 0, At, B0); BAR;
;     LDB(B1, 0, 1); BAR; WAIT_L(0); MMA(0, 1, At, B1); BAR;
	s_waitcnt lgkmcnt(0)
	s_setprio 1
	s_waitcnt lgkmcnt(0)
	v_mfma_f32_16x16x32_bf16 v[60:63], v[184:187], v[168:171], v[60:63]
	v_mfma_f32_16x16x32_bf16 v[56:59], v[184:187], v[176:179], v[56:59]
	v_mfma_f32_16x16x32_bf16 v[52:55], v[192:195], v[168:171], v[52:55]
	v_mfma_f32_16x16x32_bf16 v[48:51], v[192:195], v[176:179], v[48:51]
	v_mfma_f32_16x16x32_bf16 v[44:47], v[200:203], v[168:171], v[44:47]
	v_mfma_f32_16x16x32_bf16 v[40:43], v[200:203], v[176:179], v[40:43]
	v_mfma_f32_16x16x32_bf16 v[36:39], v[222:225], v[168:171], v[36:39]
	v_mfma_f32_16x16x32_bf16 v[32:35], v[222:225], v[176:179], v[32:35]
	v_mfma_f32_16x16x32_bf16 v[60:63], v[188:191], v[172:175], v[60:63]
	v_mfma_f32_16x16x32_bf16 v[56:59], v[188:191], v[180:183], v[56:59]
	v_mfma_f32_16x16x32_bf16 v[52:55], v[196:199], v[172:175], v[52:55]
	v_mfma_f32_16x16x32_bf16 v[48:51], v[196:199], v[180:183], v[48:51]
	v_mfma_f32_16x16x32_bf16 v[44:47], v[204:207], v[172:175], v[44:47]
	v_mfma_f32_16x16x32_bf16 v[40:43], v[204:207], v[180:183], v[40:43]
	v_mfma_f32_16x16x32_bf16 v[36:39], v[226:229], v[172:175], v[36:39]
	v_mfma_f32_16x16x32_bf16 v[32:35], v[226:229], v[180:183], v[32:35]
	s_setprio 0
	s_barrier
	v_readfirstlane_b32 s12, v158
	v_lshl_add_u64 v[168:169], v[216:217], 0, s[60:61]
	s_mov_b32 m0, s12
	v_readfirstlane_b32 s12, v160
	global_load_lds_dwordx4 v[168:169], off
	v_lshl_add_u64 v[168:169], v[218:219], 0, s[60:61]
	s_mov_b32 m0, s12
	s_nop 0
	global_load_lds_dwordx4 v[168:169], off
	s_waitcnt vmcnt(6)
	s_barrier
	s_setprio 1
	v_mfma_f32_16x16x32_bf16 v[28:31], v[184:187], v[230:233], v[28:31]
	v_mfma_f32_16x16x32_bf16 v[24:27], v[184:187], v[238:241], v[24:27]
	v_mfma_f32_16x16x32_bf16 v[20:23], v[192:195], v[230:233], v[20:23]
	v_mfma_f32_16x16x32_bf16 v[16:19], v[192:195], v[238:241], v[16:19]
	v_mfma_f32_16x16x32_bf16 v[12:15], v[200:203], v[230:233], v[12:15]
	v_mfma_f32_16x16x32_bf16 v[8:11], v[200:203], v[238:241], v[8:11]
	v_mfma_f32_16x16x32_bf16 v[4:7], v[222:225], v[230:233], v[4:7]
	v_mfma_f32_16x16x32_bf16 v[0:3], v[222:225], v[238:241], v[0:3]
	v_mfma_f32_16x16x32_bf16 v[28:31], v[188:191], v[234:237], v[28:31]
	v_mfma_f32_16x16x32_bf16 v[24:27], v[188:191], v[242:245], v[24:27]
	v_mfma_f32_16x16x32_bf16 v[20:23], v[196:199], v[234:237], v[20:23]
	v_mfma_f32_16x16x32_bf16 v[16:19], v[196:199], v[242:245], v[16:19]
	v_mfma_f32_16x16x32_bf16 v[12:15], v[204:207], v[234:237], v[12:15]
	v_mfma_f32_16x16x32_bf16 v[8:11], v[204:207], v[242:245], v[8:11]
	v_mfma_f32_16x16x32_bf16 v[4:7], v[226:229], v[234:237], v[4:7]
	v_mfma_f32_16x16x32_bf16 v[0:3], v[226:229], v[242:245], v[0:3]
	s_setprio 0
	s_add_i32 s11, s11, 2
	v_lshl_add_u64 v[134:135], v[134:135], 0, s[94:95]
	v_lshl_add_u64 v[136:137], v[136:137], 0, s[94:95]
	v_lshl_add_u64 v[138:139], v[138:139], 0, s[94:95]
	s_cmp_lt_u32 s11, 12
	v_lshl_add_u64 v[140:141], v[140:141], 0, s[94:95]
	s_cbranch_scc1 .LBB0_64
	s_barrier
	s_mov_b64 s[12:13], 0x780
	v_readfirstlane_b32 s11, v162
	v_lshl_add_u64 v[130:131], v[130:131], 0, s[12:13]
	s_mov_b32 m0, s11
	v_readfirstlane_b32 s11, v165
	ds_read_b128 v[134:137], v161
	ds_read_b128 v[138:141], v161 offset:1024
	ds_read_b128 v[142:145], v161 offset:2048
	ds_read_b128 v[168:171], v161 offset:3072
	ds_read_b128 v[172:175], v149
	ds_read_b128 v[176:179], v149 offset:1024
	ds_read_b128 v[180:183], v148
	ds_read_b128 v[184:187], v148 offset:1024
	ds_read_b128 v[188:191], v147
	ds_read_b128 v[192:195], v147 offset:1024
	ds_read_b128 v[196:199], v146
	ds_read_b128 v[200:203], v146 offset:1024
	global_load_lds_dwordx4 v[130:131], off
	v_lshl_add_u64 v[130:131], v[132:133], 0, s[12:13]
	s_mov_b32 m0, s11
	s_nop 0
	global_load_lds_dwordx4 v[130:131], off
	s_barrier
	s_waitcnt lgkmcnt(0)
	s_setprio 1
	s_waitcnt lgkmcnt(0)
	v_mfma_f32_16x16x32_bf16 v[126:129], v[172:175], v[134:137], v[126:129]
	v_mfma_f32_16x16x32_bf16 v[122:125], v[172:175], v[142:145], v[122:125]
	v_mfma_f32_16x16x32_bf16 v[118:121], v[180:183], v[134:137], v[118:121]
	v_mfma_f32_16x16x32_bf16 v[114:117], v[180:183], v[142:145], v[114:117]
	v_mfma_f32_16x16x32_bf16 v[110:113], v[188:191], v[134:137], v[110:113]
	v_mfma_f32_16x16x32_bf16 v[106:109], v[188:191], v[142:145], v[106:109]
	v_mfma_f32_16x16x32_bf16 v[102:105], v[196:199], v[134:137], v[102:105]
	v_mfma_f32_16x16x32_bf16 v[126:129], v[176:179], v[138:141], v[126:129]
	v_mfma_f32_16x16x32_bf16 v[122:125], v[176:179], v[168:171], v[122:125]
	v_mfma_f32_16x16x32_bf16 v[118:121], v[184:187], v[138:141], v[118:121]
	v_mfma_f32_16x16x32_bf16 v[114:117], v[184:187], v[168:171], v[114:117]
	v_mfma_f32_16x16x32_bf16 v[110:113], v[192:195], v[138:141], v[110:113]
	v_mfma_f32_16x16x32_bf16 v[106:109], v[192:195], v[168:171], v[106:109]
	v_mfma_f32_16x16x32_bf16 v[102:105], v[200:203], v[138:141], v[102:105]
	v_mfma_f32_16x16x32_bf16 v[98:101], v[196:199], v[142:145], v[98:101]
	v_mfma_f32_16x16x32_bf16 v[98:101], v[200:203], v[168:171], v[98:101]
	s_setprio 0
	s_barrier
	ds_read_b128 v[130:133], v159
	ds_read_b128 v[204:207], v159 offset:1024
	ds_read_b128 v[222:225], v159 offset:2048
	ds_read_b128 v[156:159], v159 offset:3072
	s_barrier
; #define WAIT_V(n) asm volatile("s_waitcnt vmcnt(" #n ")" ::: "memory")
; #define WAIT_L(n) asm volatile("s_waitcnt lgkmcnt(" #n ")" ::: "memory")
; #define BAR __builtin_amdgcn_s_barrier()
; template <int K>
; __device__ __forceinline__ void gemm_mainloop(const bf16* __restrict__ A, const bf16* __restrict__ Bt, int brow, int bcol,
;                                               f32x4 (&acc)[2][2][4][2], const int tidx) {
;     ...
;     LDB(B1, 0, 1); BAR; WAIT_L(0); MMA(0, 1, At, B1); BAR;
;     LDA(At, 0, 1); WAIT_V(4); BAR; WAIT_L(0); MMA(1, 0, At, B0); MMA(1, 1, At, B1); BAR; }
;   { LDB(B0, 1, 0); LDA(At, 1, 0); WAIT_V(2); BAR; WAIT_L(0); MMA(0, 0, At, B0); BAR;
	s_waitcnt lgkmcnt(0)
	s_setprio 1
	s_waitcnt lgkmcnt(0)
	v_mfma_f32_16x16x32_bf16 v[92:95], v[172:175], v[130:133], v[92:95]
	v_mfma_f32_16x16x32_bf16 v[80:83], v[180:183], v[222:225], v[80:83]
	v_mfma_f32_16x16x32_bf16 v[68:71], v[196:199], v[130:133], v[68:71]
	v_mfma_f32_16x16x32_bf16 v[92:95], v[176:179], v[204:207], v[92:95]
	v_mfma_f32_16x16x32_bf16 v[88:91], v[172:175], v[222:225], v[88:91]
	v_mfma_f32_16x16x32_bf16 v[84:87], v[180:183], v[130:133], v[84:87]
	v_mfma_f32_16x16x32_bf16 v[80:83], v[184:187], v[156:159], v[80:83]
	v_mfma_f32_16x16x32_bf16 v[76:79], v[188:191], v[130:133], v[76:79]
	v_mfma_f32_16x16x32_bf16 v[72:75], v[188:191], v[222:225], v[72:75]
	v_mfma_f32_16x16x32_bf16 v[68:71], v[200:203], v[204:207], v[68:71]
	v_mfma_f32_16x16x32_bf16 v[64:67], v[196:199], v[222:225], v[64:67]
	v_mfma_f32_16x16x32_bf16 v[88:91], v[176:179], v[156:159], v[88:91]
	v_mfma_f32_16x16x32_bf16 v[172:175], v[184:187], v[204:207], v[84:87]
	v_mfma_f32_16x16x32_bf16 v[176:179], v[192:195], v[204:207], v[76:79]
	v_mfma_f32_16x16x32_bf16 v[72:75], v[192:195], v[156:159], v[72:75]
	v_mfma_f32_16x16x32_bf16 v[64:67], v[200:203], v[156:159], v[64:67]
	s_setprio 0
	s_barrier
	ds_read_b128 v[76:79], v149 offset:16384
	ds_read_b128 v[84:87], v149 offset:17408
	ds_read_b128 v[180:183], v148 offset:16384
	ds_read_b128 v[184:187], v148 offset:17408
	ds_read_b128 v[188:191], v147 offset:16384
	ds_read_b128 v[192:195], v147 offset:17408
	ds_read_b128 v[196:199], v146 offset:16384
	ds_read_b128 v[200:203], v146 offset:17408
	s_waitcnt vmcnt(4)
	s_barrier
	s_waitcnt lgkmcnt(0)
	s_setprio 1
	s_waitcnt lgkmcnt(0)
	v_mfma_f32_16x16x32_bf16 v[56:59], v[76:79], v[142:145], v[56:59]
	v_mfma_f32_16x16x32_bf16 v[44:47], v[188:191], v[134:137], v[44:47]
	v_mfma_f32_16x16x32_bf16 v[32:35], v[196:199], v[142:145], v[32:35]
	v_mfma_f32_16x16x32_bf16 v[60:63], v[76:79], v[134:137], v[60:63]
	v_mfma_f32_16x16x32_bf16 v[56:59], v[84:87], v[168:171], v[56:59]
	v_mfma_f32_16x16x32_bf16 v[52:55], v[180:183], v[134:137], v[52:55]
	v_mfma_f32_16x16x32_bf16 v[48:51], v[180:183], v[142:145], v[48:51]
	v_mfma_f32_16x16x32_bf16 v[44:47], v[192:195], v[138:141], v[44:47]
	v_mfma_f32_16x16x32_bf16 v[40:43], v[188:191], v[142:145], v[40:43]
	v_mfma_f32_16x16x32_bf16 v[36:39], v[196:199], v[134:137], v[36:39]
	v_mfma_f32_16x16x32_bf16 v[32:35], v[200:203], v[168:171], v[32:35]
	v_mfma_f32_16x16x32_bf16 v[226:229], v[84:87], v[138:141], v[60:63]
	v_mfma_f32_16x16x32_bf16 v[230:233], v[184:187], v[138:141], v[52:55]
	v_mfma_f32_16x16x32_bf16 v[48:51], v[184:187], v[168:171], v[48:51]
	v_mfma_f32_16x16x32_bf16 v[40:43], v[192:195], v[168:171], v[40:43]
	v_mfma_f32_16x16x32_bf16 v[234:237], v[200:203], v[138:141], v[36:39]
	s_setprio 0
	s_setprio 1
	v_mfma_f32_16x16x32_bf16 v[20:23], v[180:183], v[130:133], v[20:23]
	v_mfma_f32_16x16x32_bf16 v[8:11], v[188:191], v[222:225], v[8:11]
	v_mfma_f32_16x16x32_bf16 v[28:31], v[76:79], v[130:133], v[28:31]
	v_mfma_f32_16x16x32_bf16 v[24:27], v[76:79], v[222:225], v[24:27]
	v_mfma_f32_16x16x32_bf16 v[20:23], v[184:187], v[204:207], v[20:23]
	v_mfma_f32_16x16x32_bf16 v[16:19], v[180:183], v[222:225], v[16:19]
	v_mfma_f32_16x16x32_bf16 v[12:15], v[188:191], v[130:133], v[12:15]
	v_mfma_f32_16x16x32_bf16 v[8:11], v[192:195], v[156:159], v[8:11]
	v_mfma_f32_16x16x32_bf16 v[4:7], v[196:199], v[130:133], v[4:7]
	v_mfma_f32_16x16x32_bf16 v[0:3], v[196:199], v[222:225], v[0:3]
	v_mfma_f32_16x16x32_bf16 v[168:171], v[84:87], v[204:207], v[28:31]
	v_mfma_f32_16x16x32_bf16 v[24:27], v[84:87], v[156:159], v[24:27]
	v_mfma_f32_16x16x32_bf16 v[16:19], v[184:187], v[156:159], v[16:19]
	v_mfma_f32_16x16x32_bf16 v[180:183], v[192:195], v[204:207], v[12:15]
	v_mfma_f32_16x16x32_bf16 v[184:187], v[200:203], v[204:207], v[4:7]
	v_mfma_f32_16x16x32_bf16 v[188:191], v[200:203], v[156:159], v[0:3]
	s_setprio 0
	s_barrier
	ds_read_b128 v[192:195], v150
	ds_read_b128 v[196:199], v150 offset:1024
	ds_read_b128 v[200:203], v150 offset:2048
	ds_read_b128 v[204:207], v150 offset:3072
	ds_read_b128 v[0:3], v149 offset:32768
	ds_read_b128 v[4:7], v149 offset:33792
	ds_read_b128 v[12:15], v148 offset:32768
	ds_read_b128 v[28:31], v148 offset:33792
	ds_read_b128 v[130:133], v147 offset:32768
	ds_read_b128 v[138:141], v147 offset:33792
	ds_read_b128 v[156:159], v146 offset:32768
	ds_read_b128 v[222:225], v146 offset:33792
	s_waitcnt vmcnt(2)
	s_barrier
; #define WAIT_V(n) asm volatile("s_waitcnt vmcnt(" #n ")" ::: "memory")
; #define WAIT_L(n) asm volatile("s_waitcnt lgkmcnt(" #n ")" ::: "memory")
; #define BAR __builtin_amdgcn_s_barrier()
; template <int K>
; __device__ __forceinline__ void gemm_mainloop(const bf16* __restrict__ A, const bf16* __restrict__ Bt, int brow, int bcol,
;                                               f32x4 (&acc)[2][2][4][2], const int tidx) {
;     ...
;   { LDB(B0, 1, 0); LDA(At, 1, 0); WAIT_V(2); BAR; WAIT_L(0); MMA(0, 0, At, B0); BAR;
;     LDB(B1, 1, 1); WAIT_V(0); BAR; WAIT_L(0); MMA(0, 1, At, B1); BAR;
;     LDA(At, 1, 1); BAR; WAIT_L(0); MMA(1, 0, At, B0); MMA(1, 1, At, B1); BAR; }
;   if (wr == 0) BAR;
	s_waitcnt lgkmcnt(0)
	s_setprio 1
	s_waitcnt lgkmcnt(0)
	v_mfma_f32_16x16x32_bf16 v[36:39], v[0:3], v[192:195], v[126:129]
	v_mfma_f32_16x16x32_bf16 v[150:153], v[4:7], v[196:199], v[36:39]
	v_mfma_f32_16x16x32_bf16 v[36:39], v[0:3], v[200:203], v[122:125]
	v_mfma_f32_16x16x32_bf16 v[142:145], v[4:7], v[204:207], v[36:39]
	v_mfma_f32_16x16x32_bf16 v[36:39], v[12:15], v[192:195], v[118:121]
	v_mfma_f32_16x16x32_bf16 v[134:137], v[28:31], v[196:199], v[36:39]
	v_mfma_f32_16x16x32_bf16 v[36:39], v[12:15], v[200:203], v[114:117]
	v_mfma_f32_16x16x32_bf16 v[126:129], v[28:31], v[204:207], v[36:39]
	v_mfma_f32_16x16x32_bf16 v[36:39], v[130:133], v[192:195], v[110:113]
	v_mfma_f32_16x16x32_bf16 v[118:121], v[138:141], v[196:199], v[36:39]
	v_mfma_f32_16x16x32_bf16 v[36:39], v[130:133], v[200:203], v[106:109]
	v_mfma_f32_16x16x32_bf16 v[110:113], v[138:141], v[204:207], v[36:39]
	v_mfma_f32_16x16x32_bf16 v[36:39], v[156:159], v[192:195], v[102:105]
	v_mfma_f32_16x16x32_bf16 v[102:105], v[222:225], v[196:199], v[36:39]
	v_mfma_f32_16x16x32_bf16 v[36:39], v[156:159], v[200:203], v[98:101]
	v_mfma_f32_16x16x32_bf16 v[84:87], v[222:225], v[204:207], v[36:39]
	s_setprio 0
	s_barrier
	ds_read_b128 v[98:101], v154
	ds_read_b128 v[238:241], v154 offset:1024
	ds_read_b128 v[242:245], v154 offset:2048
	ds_read_b128 v[246:249], v154 offset:3072
	s_waitcnt vmcnt(0)
	s_barrier
	s_waitcnt lgkmcnt(0)
	s_setprio 1
	s_waitcnt lgkmcnt(0)
	v_mfma_f32_16x16x32_bf16 v[36:39], v[0:3], v[98:101], v[92:95]
	v_mfma_f32_16x16x32_bf16 v[0:3], v[0:3], v[242:245], v[88:91]
	v_mfma_f32_16x16x32_bf16 v[60:63], v[4:7], v[246:249], v[0:3]
	v_mfma_f32_16x16x32_bf16 v[0:3], v[12:15], v[98:101], v[172:175]
	v_mfma_f32_16x16x32_bf16 v[52:55], v[28:31], v[238:241], v[0:3]
	v_mfma_f32_16x16x32_bf16 v[0:3], v[12:15], v[242:245], v[80:83]
	v_mfma_f32_16x16x32_bf16 v[76:79], v[4:7], v[238:241], v[36:39]
	v_mfma_f32_16x16x32_bf16 v[36:39], v[28:31], v[246:249], v[0:3]
	v_mfma_f32_16x16x32_bf16 v[0:3], v[130:133], v[98:101], v[176:179]
	v_mfma_f32_16x16x32_bf16 v[28:31], v[138:141], v[238:241], v[0:3]
	v_mfma_f32_16x16x32_bf16 v[0:3], v[130:133], v[242:245], v[72:75]
	v_mfma_f32_16x16x32_bf16 v[12:15], v[138:141], v[246:249], v[0:3]
	v_mfma_f32_16x16x32_bf16 v[0:3], v[156:159], v[98:101], v[68:71]
	v_mfma_f32_16x16x32_bf16 v[4:7], v[222:225], v[238:241], v[0:3]
	v_mfma_f32_16x16x32_bf16 v[0:3], v[156:159], v[242:245], v[64:67]
	v_mfma_f32_16x16x32_bf16 v[0:3], v[222:225], v[246:249], v[0:3]
	s_setprio 0
	s_barrier
	ds_read_b128 v[64:67], v149 offset:49152
	ds_read_b128 v[68:71], v149 offset:50176
	ds_read_b128 v[72:75], v148 offset:49152
	ds_read_b128 v[88:91], v148 offset:50176
	ds_read_b128 v[172:175], v147 offset:49152
	ds_read_b128 v[176:179], v147 offset:50176
	ds_read_b128 v[222:225], v146 offset:49152
	ds_read_b128 v[250:253], v146 offset:50176
	s_barrier
	s_waitcnt lgkmcnt(0)
	s_setprio 1
	s_waitcnt lgkmcnt(0)
	v_mfma_f32_16x16x32_bf16 v[56:59], v[64:67], v[200:203], v[56:59]
	v_mfma_f32_16x16x32_bf16 v[40:43], v[172:175], v[200:203], v[40:43]
	v_mfma_f32_16x16x32_bf16 v[80:83], v[64:67], v[192:195], v[226:229]
	v_mfma_f32_16x16x32_bf16 v[154:157], v[68:71], v[204:207], v[56:59]
	v_mfma_f32_16x16x32_bf16 v[56:59], v[72:75], v[192:195], v[230:233]
	v_mfma_f32_16x16x32_bf16 v[48:51], v[72:75], v[200:203], v[48:51]
	v_mfma_f32_16x16x32_bf16 v[44:47], v[172:175], v[192:195], v[44:47]
	v_mfma_f32_16x16x32_bf16 v[122:125], v[176:179], v[204:207], v[40:43]
	v_mfma_f32_16x16x32_bf16 v[40:43], v[222:225], v[192:195], v[234:237]
	v_mfma_f32_16x16x32_bf16 v[32:35], v[222:225], v[200:203], v[32:35]
	v_mfma_f32_16x16x32_bf16 v[158:161], v[68:71], v[196:199], v[80:83]
	v_mfma_f32_16x16x32_bf16 v[146:149], v[88:91], v[196:199], v[56:59]
	v_mfma_f32_16x16x32_bf16 v[138:141], v[88:91], v[204:207], v[48:51]
	v_mfma_f32_16x16x32_bf16 v[130:133], v[176:179], v[196:199], v[44:47]
	v_mfma_f32_16x16x32_bf16 v[114:117], v[250:253], v[196:199], v[40:43]
	v_mfma_f32_16x16x32_bf16 v[106:109], v[250:253], v[204:207], v[32:35]
	s_setprio 0
	s_setprio 1
	v_mfma_f32_16x16x32_bf16 v[32:35], v[64:67], v[98:101], v[168:171]
	v_mfma_f32_16x16x32_bf16 v[8:11], v[172:175], v[242:245], v[8:11]
	v_mfma_f32_16x16x32_bf16 v[92:95], v[68:71], v[238:241], v[32:35]
	v_mfma_f32_16x16x32_bf16 v[24:27], v[64:67], v[242:245], v[24:27]
	v_mfma_f32_16x16x32_bf16 v[20:23], v[72:75], v[98:101], v[20:23]
	v_mfma_f32_16x16x32_bf16 v[16:19], v[72:75], v[242:245], v[16:19]
	v_mfma_f32_16x16x32_bf16 v[32:35], v[176:179], v[246:249], v[8:11]
	v_mfma_f32_16x16x32_bf16 v[8:11], v[222:225], v[98:101], v[184:187]
	v_mfma_f32_16x16x32_bf16 v[80:83], v[68:71], v[246:249], v[24:27]
	v_mfma_f32_16x16x32_bf16 v[68:71], v[88:91], v[238:241], v[20:23]
	v_mfma_f32_16x16x32_bf16 v[56:59], v[88:91], v[246:249], v[16:19]
	v_mfma_f32_16x16x32_bf16 v[16:19], v[172:175], v[98:101], v[180:183]
	v_mfma_f32_16x16x32_bf16 v[20:23], v[250:253], v[238:241], v[8:11]
	v_mfma_f32_16x16x32_bf16 v[8:11], v[222:225], v[242:245], v[188:191]
	v_mfma_f32_16x16x32_bf16 v[44:47], v[176:179], v[238:241], v[16:19]
	v_mfma_f32_16x16x32_bf16 v[8:11], v[250:253], v[246:249], v[8:11]
	s_setprio 0
	v_cmp_gt_u32_e32 vcc, s50, v97
	s_barrier
	s_and_saveexec_b64 s[12:13], vcc
	s_cbranch_execz .LBB0_56
	s_barrier
	s_branch .LBB0_56

; #define WAIT_V(n) asm volatile("s_waitcnt vmcnt(" #n ")" ::: "memory")
; #define WAIT_L(n) asm volatile("s_waitcnt lgkmcnt(" #n ")" ::: "memory")
; #define BAR __builtin_amdgcn_s_barrier()
; #define SCHED __builtin_amdgcn_sched_barrier(0)
; template <int K>
; __device__ __forceinline__ void gemm_mainloop(const bf16* __restrict__ A, const bf16* __restrict__ Bt, int brow, int bcol,
;                                               f32x4 (&acc)[2][2][4][2], const int tidx) {
;     ...
;   for (int t = 0; t < nt - 2; t += 2) {
;     LDB(B0, 0, 0); SCHED; LDA(At, 0, 0); STAGE(SA(1, 1), A, brow + HALF, t + 1);
;     WAIT_L(8); BAR; WAIT_L(0); MMA(0, 0, At, B0); BAR; SCHED;
;     LDB(B1, 0, 1); STAGE(SB(0, 0), Bt, bcol, t + 2);
;     BAR; WAIT_L(0); MMA(0, 1, At, B1); BAR;
;     LDA(At, 0, 1); STAGE(SA(0, 0), A, brow, t + 2);
;     BAR; WAIT_L(0); MMA(1, 0, At, B0); BAR; SCHED;
;     STAGE(SB(0, 1), Bt, bcol + HALF, t + 2);
;     WAIT_V(6); BAR; MMA(1, 1, At, B1); BAR;
.LBB0_239:
	s_barrier
	ds_read_b128 v[174:177], v170
	ds_read_b128 v[178:181], v170 offset:1024
	ds_read_b128 v[182:185], v170 offset:2048
	ds_read_b128 v[186:189], v170 offset:3072
	v_add_u32_e32 v171, 0xc000, v156
	v_lshl_add_u64 v[250:251], v[142:143], 0, s[16:17]
	v_readfirstlane_b32 s19, v171
	v_lshl_add_u64 v[172:173], v[250:251], 0, s[20:21]
	s_mov_b32 m0, s19
	ds_read_b128 v[190:193], v154
	ds_read_b128 v[194:197], v154 offset:1024
	ds_read_b128 v[198:201], v153
	ds_read_b128 v[202:205], v153 offset:1024
	ds_read_b128 v[206:209], v152
	ds_read_b128 v[222:225], v152 offset:1024
	ds_read_b128 v[226:229], v151
	ds_read_b128 v[230:233], v151 offset:1024
	global_load_lds_dwordx4 v[172:173], off
	v_add_u32_e32 v172, 0xe000, v156
	v_lshl_add_u64 v[252:253], v[144:145], 0, s[16:17]
	v_readfirstlane_b32 s19, v172
	v_lshl_add_u64 v[234:235], v[252:253], 0, s[20:21]
	s_mov_b32 m0, s19
	s_nop 0
	global_load_lds_dwordx4 v[234:235], off
	s_waitcnt lgkmcnt(8)
	s_barrier
	s_waitcnt lgkmcnt(0)
	s_setprio 1
	s_waitcnt lgkmcnt(0)
	v_mfma_f32_16x16x32_bf16 v[126:129], v[190:193], v[174:177], v[126:129]
	v_mfma_f32_16x16x32_bf16 v[122:125], v[190:193], v[182:185], v[122:125]
	v_mfma_f32_16x16x32_bf16 v[118:121], v[198:201], v[174:177], v[118:121]
	v_mfma_f32_16x16x32_bf16 v[114:117], v[198:201], v[182:185], v[114:117]
	v_mfma_f32_16x16x32_bf16 v[110:113], v[206:209], v[174:177], v[110:113]
	v_mfma_f32_16x16x32_bf16 v[106:109], v[206:209], v[182:185], v[106:109]
	v_mfma_f32_16x16x32_bf16 v[102:105], v[226:229], v[174:177], v[102:105]
	v_mfma_f32_16x16x32_bf16 v[98:101], v[226:229], v[182:185], v[98:101]
	v_mfma_f32_16x16x32_bf16 v[126:129], v[194:197], v[178:181], v[126:129]
	v_mfma_f32_16x16x32_bf16 v[122:125], v[194:197], v[186:189], v[122:125]
	v_mfma_f32_16x16x32_bf16 v[118:121], v[202:205], v[178:181], v[118:121]
	v_mfma_f32_16x16x32_bf16 v[114:117], v[202:205], v[186:189], v[114:117]
	v_mfma_f32_16x16x32_bf16 v[110:113], v[222:225], v[178:181], v[110:113]
	v_mfma_f32_16x16x32_bf16 v[106:109], v[222:225], v[186:189], v[106:109]
	v_mfma_f32_16x16x32_bf16 v[102:105], v[230:233], v[178:181], v[102:105]
	v_mfma_f32_16x16x32_bf16 v[98:101], v[230:233], v[186:189], v[98:101]
	s_setprio 0
	s_barrier
	v_lshl_add_u64 v[216:217], v[138:139], 0, s[16:17]
	v_readfirstlane_b32 s19, v150
	v_lshl_add_u64 v[212:213], v[216:217], 0, s[94:95]
	s_mov_b32 m0, s19
	v_add_u32_e32 v173, 0x2000, v150
	ds_read_b128 v[234:237], v167
	ds_read_b128 v[238:241], v167 offset:1024
	ds_read_b128 v[242:245], v167 offset:2048
	ds_read_b128 v[246:249], v167 offset:3072
	global_load_lds_dwordx4 v[212:213], off
	v_lshl_add_u64 v[212:213], v[140:141], 0, s[16:17]
	v_readfirstlane_b32 s19, v173
	v_lshl_add_u64 v[218:219], v[212:213], 0, s[94:95]
	s_mov_b32 m0, s19
	s_nop 0
	global_load_lds_dwordx4 v[218:219], off
	s_barrier
	s_waitcnt lgkmcnt(0)
	s_setprio 1
	s_waitcnt lgkmcnt(0)
	v_mfma_f32_16x16x32_bf16 v[92:95], v[190:193], v[234:237], v[92:95]
	v_mfma_f32_16x16x32_bf16 v[88:91], v[190:193], v[242:245], v[88:91]
	v_mfma_f32_16x16x32_bf16 v[84:87], v[198:201], v[234:237], v[84:87]
	v_mfma_f32_16x16x32_bf16 v[80:83], v[198:201], v[242:245], v[80:83]
	v_mfma_f32_16x16x32_bf16 v[76:79], v[206:209], v[234:237], v[76:79]
	v_mfma_f32_16x16x32_bf16 v[72:75], v[206:209], v[242:245], v[72:75]
	v_mfma_f32_16x16x32_bf16 v[68:71], v[226:229], v[234:237], v[68:71]
	v_mfma_f32_16x16x32_bf16 v[64:67], v[226:229], v[242:245], v[64:67]
	v_mfma_f32_16x16x32_bf16 v[92:95], v[194:197], v[238:241], v[92:95]
	v_mfma_f32_16x16x32_bf16 v[88:91], v[194:197], v[246:249], v[88:91]
	v_mfma_f32_16x16x32_bf16 v[84:87], v[202:205], v[238:241], v[84:87]
	v_mfma_f32_16x16x32_bf16 v[80:83], v[202:205], v[246:249], v[80:83]
	v_mfma_f32_16x16x32_bf16 v[76:79], v[222:225], v[238:241], v[76:79]
	v_mfma_f32_16x16x32_bf16 v[72:75], v[222:225], v[246:249], v[72:75]
	v_mfma_f32_16x16x32_bf16 v[68:71], v[230:233], v[238:241], v[68:71]
	v_mfma_f32_16x16x32_bf16 v[64:67], v[230:233], v[246:249], v[64:67]
	s_setprio 0
	v_readfirstlane_b32 s19, v156
	v_lshl_add_u64 v[218:219], v[250:251], 0, s[94:95]
	s_mov_b32 m0, s19
	v_readfirstlane_b32 s19, v157
	s_barrier
	ds_read_b128 v[190:193], v154 offset:16384
	ds_read_b128 v[194:197], v154 offset:17408
	ds_read_b128 v[198:201], v153 offset:16384
	ds_read_b128 v[202:205], v153 offset:17408
	ds_read_b128 v[206:209], v152 offset:16384
	ds_read_b128 v[222:225], v152 offset:17408
	ds_read_b128 v[226:229], v151 offset:16384
	ds_read_b128 v[230:233], v151 offset:17408
	global_load_lds_dwordx4 v[218:219], off
	v_lshl_add_u64 v[218:219], v[252:253], 0, s[94:95]
	s_mov_b32 m0, s19
	s_nop 0
	global_load_lds_dwordx4 v[218:219], off
	s_barrier
	s_waitcnt lgkmcnt(0)
	s_setprio 1
	s_waitcnt lgkmcnt(0)
	v_mfma_f32_16x16x32_bf16 v[60:63], v[190:193], v[174:177], v[60:63]
	v_mfma_f32_16x16x32_bf16 v[56:59], v[190:193], v[182:185], v[56:59]
	v_mfma_f32_16x16x32_bf16 v[52:55], v[198:201], v[174:177], v[52:55]
	v_mfma_f32_16x16x32_bf16 v[48:51], v[198:201], v[182:185], v[48:51]
	v_mfma_f32_16x16x32_bf16 v[44:47], v[206:209], v[174:177], v[44:47]
	v_mfma_f32_16x16x32_bf16 v[40:43], v[206:209], v[182:185], v[40:43]
	v_mfma_f32_16x16x32_bf16 v[36:39], v[226:229], v[174:177], v[36:39]
	v_mfma_f32_16x16x32_bf16 v[32:35], v[226:229], v[182:185], v[32:35]
	v_mfma_f32_16x16x32_bf16 v[60:63], v[194:197], v[178:181], v[60:63]
	v_mfma_f32_16x16x32_bf16 v[56:59], v[194:197], v[186:189], v[56:59]
	v_mfma_f32_16x16x32_bf16 v[52:55], v[202:205], v[178:181], v[52:55]
	v_mfma_f32_16x16x32_bf16 v[48:51], v[202:205], v[186:189], v[48:51]
	v_mfma_f32_16x16x32_bf16 v[44:47], v[222:225], v[178:181], v[44:47]
	v_mfma_f32_16x16x32_bf16 v[40:43], v[222:225], v[186:189], v[40:43]
	v_mfma_f32_16x16x32_bf16 v[36:39], v[230:233], v[178:181], v[36:39]
	v_mfma_f32_16x16x32_bf16 v[32:35], v[230:233], v[186:189], v[32:35]
	s_setprio 0
	s_barrier
; #define WAIT_V(n) asm volatile("s_waitcnt vmcnt(" #n ")" ::: "memory")
; #define WAIT_L(n) asm volatile("s_waitcnt lgkmcnt(" #n ")" ::: "memory")
; #define BAR __builtin_amdgcn_s_barrier()
; #define SCHED __builtin_amdgcn_sched_barrier(0)
; template <int K>
; __device__ __forceinline__ void gemm_mainloop(const bf16* __restrict__ A, const bf16* __restrict__ Bt, int brow, int bcol,
;                                               f32x4 (&acc)[2][2][4][2], const int tidx) {
;     ...
;     STAGE(SB(0, 1), Bt, bcol + HALF, t + 2);
;     WAIT_V(6); BAR; MMA(1, 1, At, B1); BAR;
;     LDB(B0, 1, 0); SCHED; LDA(At, 1, 0); STAGE(SA(0, 1), A, brow + HALF, t + 2);
;     WAIT_L(8); BAR; WAIT_L(0); MMA(0, 0, At, B0); BAR; SCHED;
;     LDB(B1, 1, 1); STAGE(SB(1, 0), Bt, bcol, t + 3);
;     BAR; WAIT_L(0); MMA(0, 1, At, B1); BAR;
;     LDA(At, 1, 1); STAGE(SA(1, 0), A, brow, t + 3);
	v_readfirstlane_b32 s19, v159
	v_add_u32_e32 v173, 0x2000, v159
	v_lshl_add_u64 v[174:175], v[216:217], 0, s[90:91]
	s_mov_b32 m0, s19
	v_readfirstlane_b32 s19, v173
	global_load_lds_dwordx4 v[174:175], off
	v_lshl_add_u64 v[174:175], v[212:213], 0, s[90:91]
	s_mov_b32 m0, s19
	s_nop 0
	global_load_lds_dwordx4 v[174:175], off
	s_waitcnt vmcnt(6)
	s_barrier
	s_setprio 1
	v_mfma_f32_16x16x32_bf16 v[28:31], v[190:193], v[234:237], v[28:31]
	v_mfma_f32_16x16x32_bf16 v[24:27], v[190:193], v[242:245], v[24:27]
	v_mfma_f32_16x16x32_bf16 v[20:23], v[198:201], v[234:237], v[20:23]
	v_mfma_f32_16x16x32_bf16 v[16:19], v[198:201], v[242:245], v[16:19]
	v_mfma_f32_16x16x32_bf16 v[12:15], v[206:209], v[234:237], v[12:15]
	v_mfma_f32_16x16x32_bf16 v[8:11], v[206:209], v[242:245], v[8:11]
	v_mfma_f32_16x16x32_bf16 v[4:7], v[226:229], v[234:237], v[4:7]
	v_mfma_f32_16x16x32_bf16 v[0:3], v[226:229], v[242:245], v[0:3]
	v_mfma_f32_16x16x32_bf16 v[28:31], v[194:197], v[238:241], v[28:31]
	v_mfma_f32_16x16x32_bf16 v[24:27], v[194:197], v[246:249], v[24:27]
	v_mfma_f32_16x16x32_bf16 v[20:23], v[202:205], v[238:241], v[20:23]
	v_mfma_f32_16x16x32_bf16 v[16:19], v[202:205], v[246:249], v[16:19]
	v_mfma_f32_16x16x32_bf16 v[12:15], v[222:225], v[238:241], v[12:15]
	v_mfma_f32_16x16x32_bf16 v[8:11], v[222:225], v[246:249], v[8:11]
	v_mfma_f32_16x16x32_bf16 v[4:7], v[230:233], v[238:241], v[4:7]
	v_mfma_f32_16x16x32_bf16 v[0:3], v[230:233], v[246:249], v[0:3]
	s_setprio 0
	s_barrier
	ds_read_b128 v[174:177], v158
	ds_read_b128 v[178:181], v158 offset:1024
	ds_read_b128 v[182:185], v158 offset:2048
	ds_read_b128 v[186:189], v158 offset:3072
	v_readfirstlane_b32 s19, v160
	v_lshl_add_u64 v[218:219], v[250:251], 0, s[90:91]
	s_mov_b32 m0, s19
	v_readfirstlane_b32 s19, v161
	ds_read_b128 v[190:193], v154 offset:32768
	ds_read_b128 v[194:197], v154 offset:33792
	ds_read_b128 v[198:201], v153 offset:32768
	ds_read_b128 v[202:205], v153 offset:33792
	ds_read_b128 v[206:209], v152 offset:32768
	ds_read_b128 v[222:225], v152 offset:33792
	ds_read_b128 v[226:229], v151 offset:32768
	ds_read_b128 v[230:233], v151 offset:33792
	global_load_lds_dwordx4 v[218:219], off
	v_lshl_add_u64 v[218:219], v[252:253], 0, s[90:91]
	s_mov_b32 m0, s19
	s_nop 0
	global_load_lds_dwordx4 v[218:219], off
	s_waitcnt lgkmcnt(8)
	s_barrier
	s_waitcnt lgkmcnt(0)
	s_setprio 1
	s_waitcnt lgkmcnt(0)
	v_mfma_f32_16x16x32_bf16 v[126:129], v[190:193], v[174:177], v[126:129]
	v_mfma_f32_16x16x32_bf16 v[122:125], v[190:193], v[182:185], v[122:125]
	v_mfma_f32_16x16x32_bf16 v[118:121], v[198:201], v[174:177], v[118:121]
	v_mfma_f32_16x16x32_bf16 v[114:117], v[198:201], v[182:185], v[114:117]
	v_mfma_f32_16x16x32_bf16 v[110:113], v[206:209], v[174:177], v[110:113]
	v_mfma_f32_16x16x32_bf16 v[106:109], v[206:209], v[182:185], v[106:109]
	v_mfma_f32_16x16x32_bf16 v[102:105], v[226:229], v[174:177], v[102:105]
	v_mfma_f32_16x16x32_bf16 v[98:101], v[226:229], v[182:185], v[98:101]
	v_mfma_f32_16x16x32_bf16 v[126:129], v[194:197], v[178:181], v[126:129]
	v_mfma_f32_16x16x32_bf16 v[122:125], v[194:197], v[186:189], v[122:125]
	v_mfma_f32_16x16x32_bf16 v[118:121], v[202:205], v[178:181], v[118:121]
	v_mfma_f32_16x16x32_bf16 v[114:117], v[202:205], v[186:189], v[114:117]
	v_mfma_f32_16x16x32_bf16 v[110:113], v[222:225], v[178:181], v[110:113]
	v_mfma_f32_16x16x32_bf16 v[106:109], v[222:225], v[186:189], v[106:109]
	v_mfma_f32_16x16x32_bf16 v[102:105], v[230:233], v[178:181], v[102:105]
	v_mfma_f32_16x16x32_bf16 v[98:101], v[230:233], v[186:189], v[98:101]
	s_setprio 0
	s_barrier
	v_readfirstlane_b32 s19, v162
	v_lshl_add_u64 v[218:219], v[216:217], 0, s[2:3]
	s_mov_b32 m0, s19
	v_readfirstlane_b32 s19, v164
	ds_read_b128 v[234:237], v155
	ds_read_b128 v[238:241], v155 offset:1024
	ds_read_b128 v[242:245], v155 offset:2048
	ds_read_b128 v[246:249], v155 offset:3072
	global_load_lds_dwordx4 v[218:219], off
	v_lshl_add_u64 v[218:219], v[212:213], 0, s[2:3]
	s_mov_b32 m0, s19
	s_nop 0
	global_load_lds_dwordx4 v[218:219], off
	s_barrier
	s_waitcnt lgkmcnt(0)
	s_setprio 1
	s_waitcnt lgkmcnt(0)
	v_mfma_f32_16x16x32_bf16 v[92:95], v[190:193], v[234:237], v[92:95]
	v_mfma_f32_16x16x32_bf16 v[88:91], v[190:193], v[242:245], v[88:91]
	v_mfma_f32_16x16x32_bf16 v[84:87], v[198:201], v[234:237], v[84:87]
	v_mfma_f32_16x16x32_bf16 v[80:83], v[198:201], v[242:245], v[80:83]
	v_mfma_f32_16x16x32_bf16 v[76:79], v[206:209], v[234:237], v[76:79]
	v_mfma_f32_16x16x32_bf16 v[72:75], v[206:209], v[242:245], v[72:75]
	v_mfma_f32_16x16x32_bf16 v[68:71], v[226:229], v[234:237], v[68:71]
	v_mfma_f32_16x16x32_bf16 v[64:67], v[226:229], v[242:245], v[64:67]
	v_mfma_f32_16x16x32_bf16 v[92:95], v[194:197], v[238:241], v[92:95]
	v_mfma_f32_16x16x32_bf16 v[88:91], v[194:197], v[246:249], v[88:91]
	v_mfma_f32_16x16x32_bf16 v[84:87], v[202:205], v[238:241], v[84:87]
	v_mfma_f32_16x16x32_bf16 v[80:83], v[202:205], v[246:249], v[80:83]
	v_mfma_f32_16x16x32_bf16 v[76:79], v[222:225], v[238:241], v[76:79]
	v_mfma_f32_16x16x32_bf16 v[72:75], v[222:225], v[246:249], v[72:75]
	v_mfma_f32_16x16x32_bf16 v[68:71], v[230:233], v[238:241], v[68:71]
	v_mfma_f32_16x16x32_bf16 v[64:67], v[230:233], v[246:249], v[64:67]
	s_setprio 0
	v_readfirstlane_b32 s19, v165
	v_lshl_add_u64 v[218:219], v[250:251], 0, s[2:3]
	s_mov_b32 m0, s19
	v_readfirstlane_b32 s19, v166
	s_barrier
	ds_read_b128 v[190:193], v154 offset:49152
	ds_read_b128 v[194:197], v154 offset:50176
	ds_read_b128 v[198:201], v153 offset:49152
	ds_read_b128 v[202:205], v153 offset:50176
	ds_read_b128 v[206:209], v152 offset:49152
	ds_read_b128 v[222:225], v152 offset:50176
	ds_read_b128 v[226:229], v151 offset:49152
	ds_read_b128 v[230:233], v151 offset:50176
	global_load_lds_dwordx4 v[218:219], off
	v_lshl_add_u64 v[218:219], v[252:253], 0, s[2:3]
	s_mov_b32 m0, s19
	s_nop 0
	global_load_lds_dwordx4 v[218:219], off
	s_barrier
; #define WAIT_V(n) asm volatile("s_waitcnt vmcnt(" #n ")" ::: "memory")
; #define WAIT_L(n) asm volatile("s_waitcnt lgkmcnt(" #n ")" ::: "memory")
; #define BAR __builtin_amdgcn_s_barrier()
; #define SCHED __builtin_amdgcn_sched_barrier(0)
; template <int K>
; __device__ __forceinline__ void gemm_mainloop(const bf16* __restrict__ A, const bf16* __restrict__ Bt, int brow, int bcol,
;                                               f32x4 (&acc)[2][2][4][2], const int tidx) {
;     ...
;     BAR; WAIT_L(0); MMA(1, 0, At, B0); BAR; SCHED;
;     STAGE(SB(1, 1), Bt, bcol + HALF, t + 3);
;     WAIT_V(6); BAR; MMA(1, 1, At, B1); BAR;
;   }
;   { LDB(B0, 0, 0); LDA(At, 0, 0); STAGE(SA(1, 1), A, brow + HALF, nt - 1);
;     BAR; WAIT_L(0); MMA(0, 0, At, B0); BAR;
;     LDB(B1, 0, 1); BAR; WAIT_L(0); MMA(0, 1, At, B1); BAR;
	s_waitcnt lgkmcnt(0)
	s_setprio 1
	s_waitcnt lgkmcnt(0)
	v_mfma_f32_16x16x32_bf16 v[60:63], v[190:193], v[174:177], v[60:63]
	v_mfma_f32_16x16x32_bf16 v[56:59], v[190:193], v[182:185], v[56:59]
	v_mfma_f32_16x16x32_bf16 v[52:55], v[198:201], v[174:177], v[52:55]
	v_mfma_f32_16x16x32_bf16 v[48:51], v[198:201], v[182:185], v[48:51]
	v_mfma_f32_16x16x32_bf16 v[44:47], v[206:209], v[174:177], v[44:47]
	v_mfma_f32_16x16x32_bf16 v[40:43], v[206:209], v[182:185], v[40:43]
	v_mfma_f32_16x16x32_bf16 v[36:39], v[226:229], v[174:177], v[36:39]
	v_mfma_f32_16x16x32_bf16 v[32:35], v[226:229], v[182:185], v[32:35]
	v_mfma_f32_16x16x32_bf16 v[60:63], v[194:197], v[178:181], v[60:63]
	v_mfma_f32_16x16x32_bf16 v[56:59], v[194:197], v[186:189], v[56:59]
	v_mfma_f32_16x16x32_bf16 v[52:55], v[202:205], v[178:181], v[52:55]
	v_mfma_f32_16x16x32_bf16 v[48:51], v[202:205], v[186:189], v[48:51]
	v_mfma_f32_16x16x32_bf16 v[44:47], v[222:225], v[178:181], v[44:47]
	v_mfma_f32_16x16x32_bf16 v[40:43], v[222:225], v[186:189], v[40:43]
	v_mfma_f32_16x16x32_bf16 v[36:39], v[230:233], v[178:181], v[36:39]
	v_mfma_f32_16x16x32_bf16 v[32:35], v[230:233], v[186:189], v[32:35]
	s_setprio 0
	s_barrier
	v_readfirstlane_b32 s19, v168
	v_lshl_add_u64 v[174:175], v[216:217], 0, s[4:5]
	s_mov_b32 m0, s19
	v_readfirstlane_b32 s19, v169
	global_load_lds_dwordx4 v[174:175], off
	v_lshl_add_u64 v[174:175], v[212:213], 0, s[4:5]
	s_mov_b32 m0, s19
	s_nop 0
	global_load_lds_dwordx4 v[174:175], off
	s_waitcnt vmcnt(6)
	s_barrier
	s_setprio 1
	v_mfma_f32_16x16x32_bf16 v[28:31], v[190:193], v[234:237], v[28:31]
	v_mfma_f32_16x16x32_bf16 v[24:27], v[190:193], v[242:245], v[24:27]
	v_mfma_f32_16x16x32_bf16 v[20:23], v[198:201], v[234:237], v[20:23]
	v_mfma_f32_16x16x32_bf16 v[16:19], v[198:201], v[242:245], v[16:19]
	v_mfma_f32_16x16x32_bf16 v[12:15], v[206:209], v[234:237], v[12:15]
	v_mfma_f32_16x16x32_bf16 v[8:11], v[206:209], v[242:245], v[8:11]
	v_mfma_f32_16x16x32_bf16 v[4:7], v[226:229], v[234:237], v[4:7]
	v_mfma_f32_16x16x32_bf16 v[0:3], v[226:229], v[242:245], v[0:3]
	v_mfma_f32_16x16x32_bf16 v[28:31], v[194:197], v[238:241], v[28:31]
	v_mfma_f32_16x16x32_bf16 v[24:27], v[194:197], v[246:249], v[24:27]
	v_mfma_f32_16x16x32_bf16 v[20:23], v[202:205], v[238:241], v[20:23]
	v_mfma_f32_16x16x32_bf16 v[16:19], v[202:205], v[246:249], v[16:19]
	v_mfma_f32_16x16x32_bf16 v[12:15], v[222:225], v[238:241], v[12:15]
	v_mfma_f32_16x16x32_bf16 v[8:11], v[222:225], v[246:249], v[8:11]
	v_mfma_f32_16x16x32_bf16 v[4:7], v[230:233], v[238:241], v[4:7]
	v_mfma_f32_16x16x32_bf16 v[0:3], v[230:233], v[246:249], v[0:3]
	s_setprio 0
	s_add_i32 s18, s18, 2
	s_add_u32 s16, s16, 0x100
	s_addc_u32 s17, s17, 0
	s_cmp_lt_u32 s18, 60
	s_cbranch_scc1 .LBB0_239
	s_barrier
	s_add_u32 s14, s14, 0x1f80
	s_addc_u32 s15, s15, 0
	v_lshl_add_u64 v[132:133], s[14:15], 0, v[132:133]
	v_readfirstlane_b32 s16, v171
	v_lshl_add_u64 v[130:131], v[130:131], 1, v[132:133]
	s_mov_b32 m0, s16
	ds_read_b128 v[138:141], v170
	ds_read_b128 v[142:145], v170 offset:1024
	ds_read_b128 v[174:177], v170 offset:2048
	ds_read_b128 v[178:181], v170 offset:3072
	ds_read_b128 v[182:185], v154
	ds_read_b128 v[186:189], v154 offset:1024
	ds_read_b128 v[190:193], v153
	ds_read_b128 v[194:197], v153 offset:1024
	ds_read_b128 v[198:201], v152
	ds_read_b128 v[202:205], v152 offset:1024
	ds_read_b128 v[206:209], v151
	ds_read_b128 v[222:225], v151 offset:1024
	global_load_lds_dwordx4 v[130:131], off
	v_lshl_add_u64 v[130:131], s[14:15], 0, v[136:137]
	v_readfirstlane_b32 s14, v172
	v_lshl_add_u64 v[130:131], v[134:135], 1, v[130:131]
	s_mov_b32 m0, s14
	s_nop 0
	global_load_lds_dwordx4 v[130:131], off
	s_barrier
	s_waitcnt lgkmcnt(0)
	s_setprio 1
	s_waitcnt lgkmcnt(0)
	v_mfma_f32_16x16x32_bf16 v[126:129], v[182:185], v[138:141], v[126:129]
	v_mfma_f32_16x16x32_bf16 v[122:125], v[182:185], v[174:177], v[122:125]
	v_mfma_f32_16x16x32_bf16 v[118:121], v[190:193], v[138:141], v[118:121]
	v_mfma_f32_16x16x32_bf16 v[114:117], v[190:193], v[174:177], v[114:117]
	v_mfma_f32_16x16x32_bf16 v[110:113], v[198:201], v[138:141], v[110:113]
	v_mfma_f32_16x16x32_bf16 v[106:109], v[198:201], v[174:177], v[106:109]
	v_mfma_f32_16x16x32_bf16 v[102:105], v[206:209], v[138:141], v[102:105]
	v_mfma_f32_16x16x32_bf16 v[98:101], v[206:209], v[174:177], v[98:101]
	v_mfma_f32_16x16x32_bf16 v[126:129], v[186:189], v[142:145], v[126:129]
	v_mfma_f32_16x16x32_bf16 v[122:125], v[186:189], v[178:181], v[122:125]
	v_mfma_f32_16x16x32_bf16 v[118:121], v[194:197], v[142:145], v[118:121]
	v_mfma_f32_16x16x32_bf16 v[114:117], v[194:197], v[178:181], v[114:117]
	v_mfma_f32_16x16x32_bf16 v[110:113], v[202:205], v[142:145], v[110:113]
	v_mfma_f32_16x16x32_bf16 v[106:109], v[202:205], v[178:181], v[106:109]
	v_mfma_f32_16x16x32_bf16 v[102:105], v[222:225], v[142:145], v[102:105]
	v_mfma_f32_16x16x32_bf16 v[98:101], v[222:225], v[178:181], v[98:101]
	s_setprio 0
	s_barrier
	ds_read_b128 v[130:133], v167
	ds_read_b128 v[134:137], v167 offset:1024
	ds_read_b128 v[168:171], v167 offset:2048
	ds_read_b128 v[164:167], v167 offset:3072
	s_barrier
; #define WAIT_V(n) asm volatile("s_waitcnt vmcnt(" #n ")" ::: "memory")
; #define WAIT_L(n) asm volatile("s_waitcnt lgkmcnt(" #n ")" ::: "memory")
; #define BAR __builtin_amdgcn_s_barrier()
; template <int K>
; __device__ __forceinline__ void gemm_mainloop(const bf16* __restrict__ A, const bf16* __restrict__ Bt, int brow, int bcol,
;                                               f32x4 (&acc)[2][2][4][2], const int tidx) {
;     ...
;     LDB(B1, 0, 1); BAR; WAIT_L(0); MMA(0, 1, At, B1); BAR;
;     LDA(At, 0, 1); WAIT_V(4); BAR; WAIT_L(0); MMA(1, 0, At, B0); MMA(1, 1, At, B1); BAR; }
;   { LDB(B0, 1, 0); LDA(At, 1, 0); WAIT_V(2); BAR; WAIT_L(0); MMA(0, 0, At, B0); BAR;
	s_waitcnt lgkmcnt(0)
	s_setprio 1
	s_waitcnt lgkmcnt(0)
	v_mfma_f32_16x16x32_bf16 v[92:95], v[182:185], v[130:133], v[92:95]
	v_mfma_f32_16x16x32_bf16 v[88:91], v[182:185], v[168:171], v[88:91]
	v_mfma_f32_16x16x32_bf16 v[84:87], v[190:193], v[130:133], v[84:87]
	v_mfma_f32_16x16x32_bf16 v[80:83], v[190:193], v[168:171], v[80:83]
	v_mfma_f32_16x16x32_bf16 v[76:79], v[198:201], v[130:133], v[76:79]
	v_mfma_f32_16x16x32_bf16 v[72:75], v[198:201], v[168:171], v[72:75]
	v_mfma_f32_16x16x32_bf16 v[68:71], v[206:209], v[130:133], v[68:71]
	v_mfma_f32_16x16x32_bf16 v[64:67], v[206:209], v[168:171], v[64:67]
	v_mfma_f32_16x16x32_bf16 v[92:95], v[186:189], v[134:137], v[92:95]
	v_mfma_f32_16x16x32_bf16 v[88:91], v[186:189], v[164:167], v[88:91]
	v_mfma_f32_16x16x32_bf16 v[84:87], v[194:197], v[134:137], v[84:87]
	v_mfma_f32_16x16x32_bf16 v[80:83], v[194:197], v[164:167], v[80:83]
	v_mfma_f32_16x16x32_bf16 v[76:79], v[202:205], v[134:137], v[76:79]
	v_mfma_f32_16x16x32_bf16 v[72:75], v[202:205], v[164:167], v[72:75]
	v_mfma_f32_16x16x32_bf16 v[68:71], v[222:225], v[134:137], v[68:71]
	v_mfma_f32_16x16x32_bf16 v[64:67], v[222:225], v[164:167], v[64:67]
	s_setprio 0
	s_barrier
	ds_read_b128 v[182:185], v154 offset:16384
	ds_read_b128 v[186:189], v154 offset:17408
	ds_read_b128 v[190:193], v153 offset:16384
	ds_read_b128 v[194:197], v153 offset:17408
	ds_read_b128 v[198:201], v152 offset:16384
	ds_read_b128 v[202:205], v152 offset:17408
	ds_read_b128 v[206:209], v151 offset:16384
	ds_read_b128 v[222:225], v151 offset:17408
	s_waitcnt vmcnt(4)
	s_barrier
	s_waitcnt lgkmcnt(0)
	s_setprio 1
	s_waitcnt lgkmcnt(0)
	v_mfma_f32_16x16x32_bf16 v[60:63], v[182:185], v[138:141], v[60:63]
	v_mfma_f32_16x16x32_bf16 v[56:59], v[182:185], v[174:177], v[56:59]
	v_mfma_f32_16x16x32_bf16 v[52:55], v[190:193], v[138:141], v[52:55]
	v_mfma_f32_16x16x32_bf16 v[48:51], v[190:193], v[174:177], v[48:51]
	v_mfma_f32_16x16x32_bf16 v[44:47], v[198:201], v[138:141], v[44:47]
	v_mfma_f32_16x16x32_bf16 v[40:43], v[198:201], v[174:177], v[40:43]
	v_mfma_f32_16x16x32_bf16 v[36:39], v[206:209], v[138:141], v[36:39]
	v_mfma_f32_16x16x32_bf16 v[32:35], v[206:209], v[174:177], v[32:35]
	v_mfma_f32_16x16x32_bf16 v[60:63], v[186:189], v[142:145], v[60:63]
	v_mfma_f32_16x16x32_bf16 v[56:59], v[186:189], v[178:181], v[56:59]
	v_mfma_f32_16x16x32_bf16 v[52:55], v[194:197], v[142:145], v[52:55]
	v_mfma_f32_16x16x32_bf16 v[48:51], v[194:197], v[178:181], v[48:51]
	v_mfma_f32_16x16x32_bf16 v[44:47], v[202:205], v[142:145], v[44:47]
	v_mfma_f32_16x16x32_bf16 v[40:43], v[202:205], v[178:181], v[40:43]
	v_mfma_f32_16x16x32_bf16 v[36:39], v[222:225], v[142:145], v[36:39]
	v_mfma_f32_16x16x32_bf16 v[32:35], v[222:225], v[178:181], v[32:35]
	s_setprio 0
	s_setprio 1
	v_mfma_f32_16x16x32_bf16 v[28:31], v[182:185], v[130:133], v[28:31]
	v_mfma_f32_16x16x32_bf16 v[24:27], v[182:185], v[168:171], v[24:27]
	v_mfma_f32_16x16x32_bf16 v[20:23], v[190:193], v[130:133], v[20:23]
	v_mfma_f32_16x16x32_bf16 v[16:19], v[190:193], v[168:171], v[16:19]
	v_mfma_f32_16x16x32_bf16 v[12:15], v[198:201], v[130:133], v[12:15]
	v_mfma_f32_16x16x32_bf16 v[8:11], v[198:201], v[168:171], v[8:11]
	v_mfma_f32_16x16x32_bf16 v[4:7], v[206:209], v[130:133], v[4:7]
	v_mfma_f32_16x16x32_bf16 v[0:3], v[206:209], v[168:171], v[0:3]
	v_mfma_f32_16x16x32_bf16 v[28:31], v[186:189], v[134:137], v[28:31]
	v_mfma_f32_16x16x32_bf16 v[24:27], v[186:189], v[164:167], v[24:27]
	v_mfma_f32_16x16x32_bf16 v[20:23], v[194:197], v[134:137], v[20:23]
	v_mfma_f32_16x16x32_bf16 v[16:19], v[194:197], v[164:167], v[16:19]
	v_mfma_f32_16x16x32_bf16 v[12:15], v[202:205], v[134:137], v[12:15]
	v_mfma_f32_16x16x32_bf16 v[8:11], v[202:205], v[164:167], v[8:11]
	v_mfma_f32_16x16x32_bf16 v[4:7], v[222:225], v[134:137], v[4:7]
	v_mfma_f32_16x16x32_bf16 v[0:3], v[222:225], v[164:167], v[0:3]
	s_setprio 0
	s_barrier
	ds_read_b128 v[130:133], v158
	ds_read_b128 v[134:137], v158 offset:1024
	ds_read_b128 v[138:141], v158 offset:2048
	ds_read_b128 v[142:145], v158 offset:3072
	ds_read_b128 v[156:159], v154 offset:32768
	ds_read_b128 v[164:167], v154 offset:33792
	ds_read_b128 v[168:171], v153 offset:32768
	ds_read_b128 v[172:175], v153 offset:33792
	ds_read_b128 v[176:179], v152 offset:32768
	ds_read_b128 v[180:183], v152 offset:33792
	ds_read_b128 v[184:187], v151 offset:32768
	ds_read_b128 v[188:191], v151 offset:33792
	s_waitcnt vmcnt(2)
	s_barrier
; #define WAIT_V(n) asm volatile("s_waitcnt vmcnt(" #n ")" ::: "memory")
; #define WAIT_L(n) asm volatile("s_waitcnt lgkmcnt(" #n ")" ::: "memory")
; #define BAR __builtin_amdgcn_s_barrier()
; template <int K>
; __device__ __forceinline__ void gemm_mainloop(const bf16* __restrict__ A, const bf16* __restrict__ Bt, int brow, int bcol,
;                                               f32x4 (&acc)[2][2][4][2], const int tidx) {
;     ...
;   { LDB(B0, 1, 0); LDA(At, 1, 0); WAIT_V(2); BAR; WAIT_L(0); MMA(0, 0, At, B0); BAR;
;     LDB(B1, 1, 1); WAIT_V(0); BAR; WAIT_L(0); MMA(0, 1, At, B1); BAR;
;     LDA(At, 1, 1); BAR; WAIT_L(0); MMA(1, 0, At, B0); MMA(1, 1, At, B1); BAR; }
;   if (wr == 0) BAR;
	s_waitcnt lgkmcnt(0)
	s_setprio 1
	s_waitcnt lgkmcnt(0)
	v_mfma_f32_16x16x32_bf16 v[126:129], v[156:159], v[130:133], v[126:129]
	v_mfma_f32_16x16x32_bf16 v[122:125], v[156:159], v[138:141], v[122:125]
	v_mfma_f32_16x16x32_bf16 v[118:121], v[168:171], v[130:133], v[118:121]
	v_mfma_f32_16x16x32_bf16 v[114:117], v[168:171], v[138:141], v[114:117]
	v_mfma_f32_16x16x32_bf16 v[110:113], v[176:179], v[130:133], v[110:113]
	v_mfma_f32_16x16x32_bf16 v[106:109], v[176:179], v[138:141], v[106:109]
	v_mfma_f32_16x16x32_bf16 v[102:105], v[184:187], v[130:133], v[102:105]
	v_mfma_f32_16x16x32_bf16 v[98:101], v[184:187], v[138:141], v[98:101]
	v_mfma_f32_16x16x32_bf16 v[126:129], v[164:167], v[134:137], v[126:129]
	v_mfma_f32_16x16x32_bf16 v[122:125], v[164:167], v[142:145], v[122:125]
	v_mfma_f32_16x16x32_bf16 v[118:121], v[172:175], v[134:137], v[118:121]
	v_mfma_f32_16x16x32_bf16 v[114:117], v[172:175], v[142:145], v[114:117]
	v_mfma_f32_16x16x32_bf16 v[110:113], v[180:183], v[134:137], v[110:113]
	v_mfma_f32_16x16x32_bf16 v[106:109], v[180:183], v[142:145], v[106:109]
	v_mfma_f32_16x16x32_bf16 v[102:105], v[188:191], v[134:137], v[102:105]
	v_mfma_f32_16x16x32_bf16 v[98:101], v[188:191], v[142:145], v[98:101]
	s_setprio 0
	s_barrier
	ds_read_b128 v[192:195], v155
	ds_read_b128 v[196:199], v155 offset:1024
	ds_read_b128 v[200:203], v155 offset:2048
	ds_read_b128 v[204:207], v155 offset:3072
	s_waitcnt vmcnt(0)
	s_barrier
	s_waitcnt lgkmcnt(0)
	s_setprio 1
	s_waitcnt lgkmcnt(0)
	v_mfma_f32_16x16x32_bf16 v[92:95], v[156:159], v[192:195], v[92:95]
	v_mfma_f32_16x16x32_bf16 v[88:91], v[156:159], v[200:203], v[88:91]
	v_mfma_f32_16x16x32_bf16 v[84:87], v[168:171], v[192:195], v[84:87]
	v_mfma_f32_16x16x32_bf16 v[80:83], v[168:171], v[200:203], v[80:83]
	v_mfma_f32_16x16x32_bf16 v[76:79], v[176:179], v[192:195], v[76:79]
	v_mfma_f32_16x16x32_bf16 v[72:75], v[176:179], v[200:203], v[72:75]
	v_mfma_f32_16x16x32_bf16 v[68:71], v[184:187], v[192:195], v[68:71]
	v_mfma_f32_16x16x32_bf16 v[64:67], v[184:187], v[200:203], v[64:67]
	v_mfma_f32_16x16x32_bf16 v[92:95], v[164:167], v[196:199], v[92:95]
	v_mfma_f32_16x16x32_bf16 v[88:91], v[164:167], v[204:207], v[88:91]
	v_mfma_f32_16x16x32_bf16 v[84:87], v[172:175], v[196:199], v[84:87]
	v_mfma_f32_16x16x32_bf16 v[80:83], v[172:175], v[204:207], v[80:83]
	v_mfma_f32_16x16x32_bf16 v[76:79], v[180:183], v[196:199], v[76:79]
	v_mfma_f32_16x16x32_bf16 v[72:75], v[180:183], v[204:207], v[72:75]
	v_mfma_f32_16x16x32_bf16 v[68:71], v[188:191], v[196:199], v[68:71]
	v_mfma_f32_16x16x32_bf16 v[64:67], v[188:191], v[204:207], v[64:67]
	s_setprio 0
	s_barrier
	ds_read_b128 v[156:159], v154 offset:49152
	ds_read_b128 v[164:167], v154 offset:50176
	ds_read_b128 v[168:171], v153 offset:49152
	ds_read_b128 v[172:175], v153 offset:50176
	ds_read_b128 v[176:179], v152 offset:49152
	ds_read_b128 v[152:155], v152 offset:50176
	ds_read_b128 v[180:183], v151 offset:49152
	ds_read_b128 v[184:187], v151 offset:50176
	s_barrier
	s_waitcnt lgkmcnt(0)
	s_setprio 1
	s_waitcnt lgkmcnt(0)
	v_mfma_f32_16x16x32_bf16 v[60:63], v[156:159], v[130:133], v[60:63]
	v_mfma_f32_16x16x32_bf16 v[56:59], v[156:159], v[138:141], v[56:59]
	v_mfma_f32_16x16x32_bf16 v[52:55], v[168:171], v[130:133], v[52:55]
	v_mfma_f32_16x16x32_bf16 v[48:51], v[168:171], v[138:141], v[48:51]
	v_mfma_f32_16x16x32_bf16 v[44:47], v[176:179], v[130:133], v[44:47]
	v_mfma_f32_16x16x32_bf16 v[40:43], v[176:179], v[138:141], v[40:43]
	v_mfma_f32_16x16x32_bf16 v[36:39], v[180:183], v[130:133], v[36:39]
	v_mfma_f32_16x16x32_bf16 v[32:35], v[180:183], v[138:141], v[32:35]
	v_mfma_f32_16x16x32_bf16 v[60:63], v[164:167], v[134:137], v[60:63]
	v_mfma_f32_16x16x32_bf16 v[56:59], v[164:167], v[142:145], v[56:59]
	v_mfma_f32_16x16x32_bf16 v[52:55], v[172:175], v[134:137], v[52:55]
	v_mfma_f32_16x16x32_bf16 v[48:51], v[172:175], v[142:145], v[48:51]
	v_mfma_f32_16x16x32_bf16 v[44:47], v[152:155], v[134:137], v[44:47]
	v_mfma_f32_16x16x32_bf16 v[40:43], v[152:155], v[142:145], v[40:43]
	v_mfma_f32_16x16x32_bf16 v[36:39], v[184:187], v[134:137], v[36:39]
	v_mfma_f32_16x16x32_bf16 v[32:35], v[184:187], v[142:145], v[32:35]
	s_setprio 0
	s_setprio 1
	v_mfma_f32_16x16x32_bf16 v[28:31], v[156:159], v[192:195], v[28:31]
	v_mfma_f32_16x16x32_bf16 v[24:27], v[156:159], v[200:203], v[24:27]
	v_mfma_f32_16x16x32_bf16 v[20:23], v[168:171], v[192:195], v[20:23]
	v_mfma_f32_16x16x32_bf16 v[16:19], v[168:171], v[200:203], v[16:19]
	v_mfma_f32_16x16x32_bf16 v[12:15], v[176:179], v[192:195], v[12:15]
	v_mfma_f32_16x16x32_bf16 v[8:11], v[176:179], v[200:203], v[8:11]
	v_mfma_f32_16x16x32_bf16 v[4:7], v[180:183], v[192:195], v[4:7]
	v_mfma_f32_16x16x32_bf16 v[0:3], v[180:183], v[200:203], v[0:3]
	v_mfma_f32_16x16x32_bf16 v[28:31], v[164:167], v[196:199], v[28:31]
	v_mfma_f32_16x16x32_bf16 v[24:27], v[164:167], v[204:207], v[24:27]
	v_mfma_f32_16x16x32_bf16 v[20:23], v[172:175], v[196:199], v[20:23]
	v_mfma_f32_16x16x32_bf16 v[16:19], v[172:175], v[204:207], v[16:19]
	v_mfma_f32_16x16x32_bf16 v[12:15], v[152:155], v[196:199], v[12:15]
	v_mfma_f32_16x16x32_bf16 v[8:11], v[152:155], v[204:207], v[8:11]
	v_mfma_f32_16x16x32_bf16 v[4:7], v[184:187], v[196:199], v[4:7]
	v_mfma_f32_16x16x32_bf16 v[0:3], v[184:187], v[204:207], v[0:3]
	s_setprio 0
	v_cmp_gt_u32_e32 vcc, s50, v146
	s_barrier
	s_and_saveexec_b64 s[14:15], vcc
	s_cbranch_execz .LBB0_242
	s_barrier
